# peel first K-loop iteration of all 7 GEMM loops (first MFMA per accumulator quad takes C=0, per-tile zeroing v_movs removed) + ctx/xattn gain-load prefetch
# speedup vs baseline: 1.1242x; 1.0054x over previous
.LBB0_289:
	s_ashr_i32 s23, s22, 31
	s_lshl_b64 s[24:25], s[22:23], 19
	s_add_u32 s24, s50, s24
	s_addc_u32 s25, s51, s25
	s_and_b64 s[26:27], s[0:1], exec
	s_cselect_b32 s19, s25, s29
	s_cselect_b32 s23, s24, s28
	s_ashr_i32 s21, s20, 31
	s_lshl_b64 s[26:27], s[20:21], 19
	s_add_u32 s26, s2, s26
	s_addc_u32 s27, s3, s27
	s_and_b64 s[30:31], s[0:1], exec
	s_cselect_b32 s21, s27, s11
	s_cselect_b32 s50, s26, s10
	s_add_u32 s28, s28, 0x40080
	s_addc_u32 s29, s29, 0
	s_add_u32 s51, s10, 0x100
	s_nop 7
	s_nop 7
	s_addc_u32 s52, s11, 0
	s_mov_b32 s53, -2
	v_readlane_b32 s57, v254, 54
	ds_read_b128 v[148:151], v158
	ds_read_b128 v[152:155], v158 offset:1024
	ds_read_b128 v[164:167], v158 offset:2048
	ds_read_b128 v[168:171], v158 offset:3072
	ds_read_b128 v[172:175], v159
	ds_read_b128 v[176:179], v159 offset:1024
	ds_read_b128 v[180:183], v159 offset:2048
	ds_read_b128 v[184:187], v159 offset:3072
	s_add_u32 s10, s28, 0xfffc0080
	s_addc_u32 s11, s29, -1
	s_cmp_eq_u32 s53, 12
	s_cselect_b32 s31, s19, s11
	s_cselect_b32 s30, s23, s10
	s_cselect_b32 s11, s21, s52
	s_cselect_b32 s10, s50, s51
	v_lshl_add_u64 v[220:221], s[28:29], 0, v[140:141]
	s_add_i32 m0, s35, 0xc000
	ds_read_b128 v[188:191], v160
	ds_read_b128 v[192:195], v160 offset:1024
	ds_read_b128 v[196:199], v160 offset:2048
	ds_read_b128 v[200:203], v160 offset:3072
	ds_read_b128 v[204:207], v160 offset:4096
	ds_read_b128 v[208:211], v160 offset:5120
	ds_read_b128 v[212:215], v160 offset:6144
	ds_read_b128 v[216:219], v160 offset:7168
	global_load_lds_dwordx4 v[220:221], off
	v_lshl_add_u64 v[220:221], s[28:29], 0, v[142:143]
	s_add_i32 m0, s35, 0xe000
	s_nop 0
	global_load_lds_dwordx4 v[220:221], off
	s_waitcnt vmcnt(8)
	s_waitcnt lgkmcnt(0)
	s_barrier
	s_setprio 1
	s_waitcnt lgkmcnt(0)
	v_mfma_f32_16x16x32_bf16 v[124:127], v[148:151], v[188:191], 0
	v_mfma_f32_16x16x32_bf16 v[116:119], v[164:167], v[188:191], 0
	v_mfma_f32_16x16x32_bf16 v[108:111], v[148:151], v[196:199], 0
	v_mfma_f32_16x16x32_bf16 v[100:103], v[164:167], v[196:199], 0
	v_mfma_f32_16x16x32_bf16 v[92:95], v[148:151], v[204:207], 0
	v_mfma_f32_16x16x32_bf16 v[84:87], v[164:167], v[204:207], 0
	v_mfma_f32_16x16x32_bf16 v[76:79], v[148:151], v[212:215], 0
	v_mfma_f32_16x16x32_bf16 v[68:71], v[164:167], v[212:215], 0
	v_mfma_f32_16x16x32_bf16 v[124:127], v[152:155], v[192:195], v[124:127]
	v_mfma_f32_16x16x32_bf16 v[116:119], v[168:171], v[192:195], v[116:119]
	v_mfma_f32_16x16x32_bf16 v[108:111], v[152:155], v[200:203], v[108:111]
	v_mfma_f32_16x16x32_bf16 v[100:103], v[168:171], v[200:203], v[100:103]
	v_mfma_f32_16x16x32_bf16 v[92:95], v[152:155], v[208:211], v[92:95]
	v_mfma_f32_16x16x32_bf16 v[84:87], v[168:171], v[208:211], v[84:87]
	v_mfma_f32_16x16x32_bf16 v[76:79], v[152:155], v[216:219], v[76:79]
	v_mfma_f32_16x16x32_bf16 v[68:71], v[168:171], v[216:219], v[68:71]
	s_setprio 0
	s_setprio 1
	v_mfma_f32_16x16x32_bf16 v[120:123], v[172:175], v[188:191], 0
	v_mfma_f32_16x16x32_bf16 v[112:115], v[180:183], v[188:191], 0
	v_mfma_f32_16x16x32_bf16 v[104:107], v[172:175], v[196:199], 0
	v_mfma_f32_16x16x32_bf16 v[96:99], v[180:183], v[196:199], 0
	v_mfma_f32_16x16x32_bf16 v[88:91], v[172:175], v[204:207], 0
	v_mfma_f32_16x16x32_bf16 v[80:83], v[180:183], v[204:207], 0
	v_mfma_f32_16x16x32_bf16 v[72:75], v[172:175], v[212:215], 0
	v_mfma_f32_16x16x32_bf16 v[64:67], v[180:183], v[212:215], 0
	v_mfma_f32_16x16x32_bf16 v[120:123], v[176:179], v[192:195], v[120:123]
	v_mfma_f32_16x16x32_bf16 v[112:115], v[184:187], v[192:195], v[112:115]
	v_mfma_f32_16x16x32_bf16 v[104:107], v[176:179], v[200:203], v[104:107]
	v_mfma_f32_16x16x32_bf16 v[96:99], v[184:187], v[200:203], v[96:99]
	v_mfma_f32_16x16x32_bf16 v[88:91], v[176:179], v[208:211], v[88:91]
	v_mfma_f32_16x16x32_bf16 v[80:83], v[184:187], v[208:211], v[80:83]
	v_mfma_f32_16x16x32_bf16 v[72:75], v[176:179], v[216:219], v[72:75]
	v_mfma_f32_16x16x32_bf16 v[64:67], v[184:187], v[216:219], v[64:67]
	s_setprio 0
	s_barrier
	s_add_i32 s54, s44, s57
	v_lshl_add_u64 v[220:221], s[10:11], 0, v[132:133]
	s_mov_b32 m0, s54
	ds_read_b128 v[188:191], v160 offset:16384
	ds_read_b128 v[192:195], v160 offset:17408
	ds_read_b128 v[196:199], v160 offset:18432
	ds_read_b128 v[200:203], v160 offset:19456
	ds_read_b128 v[204:207], v160 offset:20480
	ds_read_b128 v[208:211], v160 offset:21504
	ds_read_b128 v[212:215], v160 offset:22528
	ds_read_b128 v[216:219], v160 offset:23552
	global_load_lds_dwordx4 v[220:221], off
	s_add_i32 m0, s54, 0x2000
	s_add_u32 s54, s10, 0x40000
	v_lshl_add_u64 v[222:223], s[10:11], 0, v[128:129]
	s_addc_u32 s55, s11, 0
	s_add_i32 s56, s45, s57
	global_load_lds_dwordx4 v[222:223], off
	v_lshl_add_u64 v[224:225], s[54:55], 0, v[132:133]
	s_mov_b32 m0, s56
	v_lshl_add_u64 v[226:227], s[30:31], 0, v[130:131]
	global_load_lds_dwordx4 v[224:225], off
	v_lshl_add_u64 v[224:225], s[54:55], 0, v[128:129]
	s_add_i32 m0, s56, 0x2000
	s_nop 0
	global_load_lds_dwordx4 v[224:225], off
	v_lshl_add_u64 v[224:225], s[30:31], 0, v[134:135]
	s_mov_b32 m0, s35
	s_nop 0
	global_load_lds_dwordx4 v[224:225], off
	s_mov_b32 m0, s36
	s_nop 0
	global_load_lds_dwordx4 v[226:227], off
	s_waitcnt vmcnt(8)
	s_waitcnt lgkmcnt(0)
	s_barrier
	s_setprio 1
	s_waitcnt lgkmcnt(0)
	v_mfma_f32_16x16x32_bf16 v[60:63], v[148:151], v[188:191], 0
	v_mfma_f32_16x16x32_bf16 v[52:55], v[164:167], v[188:191], 0
	v_mfma_f32_16x16x32_bf16 v[44:47], v[148:151], v[196:199], 0
	v_mfma_f32_16x16x32_bf16 v[36:39], v[164:167], v[196:199], 0
	v_mfma_f32_16x16x32_bf16 v[28:31], v[148:151], v[204:207], 0
	v_mfma_f32_16x16x32_bf16 v[20:23], v[164:167], v[204:207], 0
	v_mfma_f32_16x16x32_bf16 v[12:15], v[148:151], v[212:215], 0
	v_mfma_f32_16x16x32_bf16 v[4:7], v[164:167], v[212:215], 0
	v_mfma_f32_16x16x32_bf16 v[60:63], v[152:155], v[192:195], v[60:63]
	v_mfma_f32_16x16x32_bf16 v[52:55], v[168:171], v[192:195], v[52:55]
	v_mfma_f32_16x16x32_bf16 v[44:47], v[152:155], v[200:203], v[44:47]
	v_mfma_f32_16x16x32_bf16 v[36:39], v[168:171], v[200:203], v[36:39]
	v_mfma_f32_16x16x32_bf16 v[28:31], v[152:155], v[208:211], v[28:31]
	v_mfma_f32_16x16x32_bf16 v[20:23], v[168:171], v[208:211], v[20:23]
	v_mfma_f32_16x16x32_bf16 v[12:15], v[152:155], v[216:219], v[12:15]
	v_mfma_f32_16x16x32_bf16 v[4:7], v[168:171], v[216:219], v[4:7]
	s_setprio 0
	s_setprio 1
	v_mfma_f32_16x16x32_bf16 v[56:59], v[172:175], v[188:191], 0
	v_mfma_f32_16x16x32_bf16 v[48:51], v[180:183], v[188:191], 0
	v_mfma_f32_16x16x32_bf16 v[40:43], v[172:175], v[196:199], 0
	v_mfma_f32_16x16x32_bf16 v[32:35], v[180:183], v[196:199], 0
	v_mfma_f32_16x16x32_bf16 v[24:27], v[172:175], v[204:207], 0
	v_mfma_f32_16x16x32_bf16 v[16:19], v[180:183], v[204:207], 0
	v_mfma_f32_16x16x32_bf16 v[8:11], v[172:175], v[212:215], 0
	v_mfma_f32_16x16x32_bf16 v[0:3], v[180:183], v[212:215], 0
	v_mfma_f32_16x16x32_bf16 v[56:59], v[176:179], v[192:195], v[56:59]
	v_mfma_f32_16x16x32_bf16 v[48:51], v[184:187], v[192:195], v[48:51]
	v_mfma_f32_16x16x32_bf16 v[40:43], v[176:179], v[200:203], v[40:43]
	v_mfma_f32_16x16x32_bf16 v[32:35], v[184:187], v[200:203], v[32:35]
	v_mfma_f32_16x16x32_bf16 v[24:27], v[176:179], v[208:211], v[24:27]
	v_mfma_f32_16x16x32_bf16 v[16:19], v[184:187], v[208:211], v[16:19]
	v_mfma_f32_16x16x32_bf16 v[8:11], v[176:179], v[216:219], v[8:11]
	v_mfma_f32_16x16x32_bf16 v[0:3], v[184:187], v[216:219], v[0:3]
	s_setprio 0
	s_barrier
	s_add_i32 s54, 0, 0x18000
	v_add_u32_e32 v136, s54, v157
	s_add_i32 s55, 0, 0x1c000
	ds_read_b128 v[148:151], v136
	ds_read_b128 v[152:155], v136 offset:1024
	ds_read_b128 v[164:167], v136 offset:2048
	ds_read_b128 v[168:171], v136 offset:3072
	v_add_u32_e32 v136, s55, v157
	ds_read_b128 v[172:175], v136
	ds_read_b128 v[176:179], v136 offset:1024
	ds_read_b128 v[180:183], v136 offset:2048
	ds_read_b128 v[184:187], v136 offset:3072
	s_add_u32 s30, s30, 0x40000
	s_addc_u32 s31, s31, 0
	s_mov_b32 m0, s37
	v_lshl_add_u64 v[228:229], s[30:31], 0, v[134:135]
	ds_read_b128 v[188:191], v160 offset:32768
	ds_read_b128 v[192:195], v160 offset:33792
	ds_read_b128 v[196:199], v160 offset:34816
	ds_read_b128 v[200:203], v160 offset:35840
	ds_read_b128 v[204:207], v160 offset:36864
	ds_read_b128 v[208:211], v160 offset:37888
	ds_read_b128 v[212:215], v160 offset:38912
	ds_read_b128 v[216:219], v160 offset:39936
	global_load_lds_dwordx4 v[228:229], off
	v_lshl_add_u64 v[228:229], s[30:31], 0, v[130:131]
	s_mov_b32 m0, s38
	s_nop 0
	global_load_lds_dwordx4 v[228:229], off
	s_waitcnt vmcnt(8)
	s_waitcnt lgkmcnt(0)
	s_barrier
	s_setprio 1
	s_waitcnt lgkmcnt(0)
	v_mfma_f32_16x16x32_bf16 v[124:127], v[148:151], v[188:191], v[124:127]
	v_mfma_f32_16x16x32_bf16 v[116:119], v[164:167], v[188:191], v[116:119]
	v_mfma_f32_16x16x32_bf16 v[108:111], v[148:151], v[196:199], v[108:111]
	v_mfma_f32_16x16x32_bf16 v[100:103], v[164:167], v[196:199], v[100:103]
	v_mfma_f32_16x16x32_bf16 v[92:95], v[148:151], v[204:207], v[92:95]
	v_mfma_f32_16x16x32_bf16 v[84:87], v[164:167], v[204:207], v[84:87]
	v_mfma_f32_16x16x32_bf16 v[76:79], v[148:151], v[212:215], v[76:79]
	v_mfma_f32_16x16x32_bf16 v[68:71], v[164:167], v[212:215], v[68:71]
	v_mfma_f32_16x16x32_bf16 v[124:127], v[152:155], v[192:195], v[124:127]
	v_mfma_f32_16x16x32_bf16 v[116:119], v[168:171], v[192:195], v[116:119]
	v_mfma_f32_16x16x32_bf16 v[108:111], v[152:155], v[200:203], v[108:111]
	v_mfma_f32_16x16x32_bf16 v[100:103], v[168:171], v[200:203], v[100:103]
	v_mfma_f32_16x16x32_bf16 v[92:95], v[152:155], v[208:211], v[92:95]
	v_mfma_f32_16x16x32_bf16 v[84:87], v[168:171], v[208:211], v[84:87]
	v_mfma_f32_16x16x32_bf16 v[76:79], v[152:155], v[216:219], v[76:79]
	v_mfma_f32_16x16x32_bf16 v[68:71], v[168:171], v[216:219], v[68:71]
	s_setprio 0
	s_setprio 1
	v_mfma_f32_16x16x32_bf16 v[120:123], v[172:175], v[188:191], v[120:123]
	v_mfma_f32_16x16x32_bf16 v[112:115], v[180:183], v[188:191], v[112:115]
	v_mfma_f32_16x16x32_bf16 v[104:107], v[172:175], v[196:199], v[104:107]
	v_mfma_f32_16x16x32_bf16 v[96:99], v[180:183], v[196:199], v[96:99]
	v_mfma_f32_16x16x32_bf16 v[88:91], v[172:175], v[204:207], v[88:91]
	v_mfma_f32_16x16x32_bf16 v[80:83], v[180:183], v[204:207], v[80:83]
	v_mfma_f32_16x16x32_bf16 v[72:75], v[172:175], v[212:215], v[72:75]
	v_mfma_f32_16x16x32_bf16 v[64:67], v[180:183], v[212:215], v[64:67]
	v_mfma_f32_16x16x32_bf16 v[120:123], v[176:179], v[192:195], v[120:123]
	v_mfma_f32_16x16x32_bf16 v[112:115], v[184:187], v[192:195], v[112:115]
	v_mfma_f32_16x16x32_bf16 v[104:107], v[176:179], v[200:203], v[104:107]
	v_mfma_f32_16x16x32_bf16 v[96:99], v[184:187], v[200:203], v[96:99]
	v_mfma_f32_16x16x32_bf16 v[88:91], v[176:179], v[208:211], v[88:91]
	v_mfma_f32_16x16x32_bf16 v[80:83], v[184:187], v[208:211], v[80:83]
	v_mfma_f32_16x16x32_bf16 v[72:75], v[176:179], v[216:219], v[72:75]
	v_mfma_f32_16x16x32_bf16 v[64:67], v[184:187], v[216:219], v[64:67]
	s_setprio 0
	s_barrier
	s_add_i32 s30, s54, s57
	v_lshl_add_u64 v[220:221], v[220:221], 0, s[14:15]
	s_mov_b32 m0, s30
	ds_read_b128 v[188:191], v160 offset:49152
	ds_read_b128 v[192:195], v160 offset:50176
	ds_read_b128 v[196:199], v160 offset:51200
	ds_read_b128 v[200:203], v160 offset:52224
	ds_read_b128 v[204:207], v160 offset:53248
	ds_read_b128 v[208:211], v160 offset:54272
	ds_read_b128 v[212:215], v160 offset:55296
	ds_read_b128 v[216:219], v160 offset:56320
	global_load_lds_dwordx4 v[220:221], off
	s_add_i32 m0, s30, 0x2000
	s_add_u32 s10, s10, 0x40080
	v_lshl_add_u64 v[220:221], v[222:223], 0, s[14:15]
	s_addc_u32 s11, s11, 0
	s_add_i32 s30, s55, s57
	global_load_lds_dwordx4 v[220:221], off
	v_lshl_add_u64 v[220:221], s[10:11], 0, v[132:133]
	s_mov_b32 m0, s30
	s_nop 0
	global_load_lds_dwordx4 v[220:221], off
	v_lshl_add_u64 v[220:221], s[10:11], 0, v[128:129]
	s_add_i32 m0, s30, 0x2000
	s_nop 0
	global_load_lds_dwordx4 v[220:221], off
	v_lshl_add_u64 v[220:221], v[224:225], 0, s[14:15]
	s_mov_b32 m0, s39
	s_nop 0
	global_load_lds_dwordx4 v[220:221], off
	v_lshl_add_u64 v[220:221], v[226:227], 0, s[14:15]
	s_mov_b32 m0, s40
	s_nop 0
	global_load_lds_dwordx4 v[220:221], off
	s_waitcnt vmcnt(8)
	s_waitcnt lgkmcnt(0)
	s_barrier
	s_setprio 1
	s_waitcnt lgkmcnt(0)
	v_mfma_f32_16x16x32_bf16 v[60:63], v[148:151], v[188:191], v[60:63]
	v_mfma_f32_16x16x32_bf16 v[52:55], v[164:167], v[188:191], v[52:55]
	v_mfma_f32_16x16x32_bf16 v[44:47], v[148:151], v[196:199], v[44:47]
	v_mfma_f32_16x16x32_bf16 v[36:39], v[164:167], v[196:199], v[36:39]
	v_mfma_f32_16x16x32_bf16 v[28:31], v[148:151], v[204:207], v[28:31]
	v_mfma_f32_16x16x32_bf16 v[20:23], v[164:167], v[204:207], v[20:23]
	v_mfma_f32_16x16x32_bf16 v[12:15], v[148:151], v[212:215], v[12:15]
	v_mfma_f32_16x16x32_bf16 v[4:7], v[164:167], v[212:215], v[4:7]
	v_mfma_f32_16x16x32_bf16 v[60:63], v[152:155], v[192:195], v[60:63]
	v_mfma_f32_16x16x32_bf16 v[52:55], v[168:171], v[192:195], v[52:55]
	v_mfma_f32_16x16x32_bf16 v[44:47], v[152:155], v[200:203], v[44:47]
	v_mfma_f32_16x16x32_bf16 v[36:39], v[168:171], v[200:203], v[36:39]
	v_mfma_f32_16x16x32_bf16 v[28:31], v[152:155], v[208:211], v[28:31]
	v_mfma_f32_16x16x32_bf16 v[20:23], v[168:171], v[208:211], v[20:23]
	v_mfma_f32_16x16x32_bf16 v[12:15], v[152:155], v[216:219], v[12:15]
	v_mfma_f32_16x16x32_bf16 v[4:7], v[168:171], v[216:219], v[4:7]
	s_setprio 0
	s_setprio 1
	v_mfma_f32_16x16x32_bf16 v[56:59], v[172:175], v[188:191], v[56:59]
	v_mfma_f32_16x16x32_bf16 v[48:51], v[180:183], v[188:191], v[48:51]
	v_mfma_f32_16x16x32_bf16 v[40:43], v[172:175], v[196:199], v[40:43]
	v_mfma_f32_16x16x32_bf16 v[32:35], v[180:183], v[196:199], v[32:35]
	v_mfma_f32_16x16x32_bf16 v[24:27], v[172:175], v[204:207], v[24:27]
	v_mfma_f32_16x16x32_bf16 v[16:19], v[180:183], v[204:207], v[16:19]
	v_mfma_f32_16x16x32_bf16 v[8:11], v[172:175], v[212:215], v[8:11]
	v_mfma_f32_16x16x32_bf16 v[0:3], v[180:183], v[212:215], v[0:3]
	v_mfma_f32_16x16x32_bf16 v[56:59], v[176:179], v[192:195], v[56:59]
	v_mfma_f32_16x16x32_bf16 v[48:51], v[184:187], v[192:195], v[48:51]
	v_mfma_f32_16x16x32_bf16 v[40:43], v[176:179], v[200:203], v[40:43]
	v_mfma_f32_16x16x32_bf16 v[32:35], v[184:187], v[200:203], v[32:35]
	v_mfma_f32_16x16x32_bf16 v[24:27], v[176:179], v[208:211], v[24:27]
	v_mfma_f32_16x16x32_bf16 v[16:19], v[184:187], v[208:211], v[16:19]
	v_mfma_f32_16x16x32_bf16 v[8:11], v[176:179], v[216:219], v[8:11]
	v_mfma_f32_16x16x32_bf16 v[0:3], v[184:187], v[216:219], v[0:3]
	s_setprio 0
	s_barrier
	s_add_i32 s53, s53, 2
	s_add_u32 s28, s28, 0x100
	s_addc_u32 s29, s29, 0
	s_add_u32 s51, s51, 0x100
	s_addc_u32 s52, s52, 0
	s_cmp_gt_u32 s53, 13

.LBB0_313:
	s_ashr_i32 s19, s18, 31
	s_lshl_b64 s[20:21], s[18:19], 19
	s_add_u32 s20, s3, s20
	s_addc_u32 s21, s30, s21
	s_and_b64 s[22:23], s[0:1], exec
	s_cselect_b32 s19, s21, s27
	s_cselect_b32 s59, s20, s26
	s_ashr_i32 s17, s16, 31
	s_lshl_b64 s[22:23], s[16:17], 19
	v_readlane_b32 s28, v254, 55
	v_readlane_b32 s29, v254, 56
	s_add_u32 s22, s28, s22
	s_addc_u32 s23, s29, s23
	s_and_b64 s[28:29], s[0:1], exec
	s_cselect_b32 s17, s23, s11
	s_cselect_b32 s60, s22, s10
	s_add_u32 s26, s26, 0x40080
	s_addc_u32 s27, s27, 0
	s_add_u32 s61, s10, 0x100
	s_nop 7
	s_nop 7
	s_addc_u32 s62, s11, 0
	s_mov_b32 s63, -2
	v_readlane_b32 s70, v254, 54
	s_waitcnt vmcnt(0)
	ds_read_b128 v[128:131], v186
	ds_read_b128 v[132:135], v186 offset:1024
	ds_read_b128 v[136:139], v186 offset:2048
	ds_read_b128 v[140:143], v186 offset:3072
	ds_read_b128 v[144:147], v187
	ds_read_b128 v[168:171], v187 offset:1024
	ds_read_b128 v[194:197], v187 offset:2048
	ds_read_b128 v[198:201], v187 offset:3072
	s_add_u32 s10, s26, 0xfffc0080
	s_addc_u32 s11, s27, -1
	s_cmp_eq_u32 s63, 12
	s_cselect_b32 s29, s19, s11
	s_cselect_b32 s28, s59, s10
	s_cselect_b32 s11, s17, s62
	s_cselect_b32 s10, s60, s61
	v_lshl_add_u64 v[234:235], s[26:27], 0, v[156:157]
	s_add_i32 m0, s25, 0xc000
	ds_read_b128 v[202:205], v188
	ds_read_b128 v[206:209], v188 offset:1024
	ds_read_b128 v[210:213], v188 offset:2048
	ds_read_b128 v[214:217], v188 offset:3072
	ds_read_b128 v[218:221], v188 offset:4096
	ds_read_b128 v[222:225], v188 offset:5120
	ds_read_b128 v[226:229], v188 offset:6144
	ds_read_b128 v[230:233], v188 offset:7168
	global_load_lds_dwordx4 v[234:235], off
	v_lshl_add_u64 v[234:235], s[26:27], 0, v[158:159]
	s_add_i32 m0, s25, 0xe000
	s_nop 0
	global_load_lds_dwordx4 v[234:235], off
	s_waitcnt vmcnt(8)
	s_waitcnt lgkmcnt(0)
	s_barrier
	s_setprio 1
	s_waitcnt lgkmcnt(0)
	v_mfma_f32_16x16x32_bf16 v[124:127], v[128:131], v[202:205], 0
	v_mfma_f32_16x16x32_bf16 v[120:123], v[136:139], v[202:205], 0
	v_mfma_f32_16x16x32_bf16 v[92:95], v[128:131], v[210:213], 0
	v_mfma_f32_16x16x32_bf16 v[88:91], v[136:139], v[210:213], 0
	v_mfma_f32_16x16x32_bf16 v[60:63], v[128:131], v[218:221], 0
	v_mfma_f32_16x16x32_bf16 v[56:59], v[136:139], v[218:221], 0
	v_mfma_f32_16x16x32_bf16 v[28:31], v[128:131], v[226:229], 0
	v_mfma_f32_16x16x32_bf16 v[24:27], v[136:139], v[226:229], 0
	v_mfma_f32_16x16x32_bf16 v[124:127], v[132:135], v[206:209], v[124:127]
	v_mfma_f32_16x16x32_bf16 v[120:123], v[140:143], v[206:209], v[120:123]
	v_mfma_f32_16x16x32_bf16 v[92:95], v[132:135], v[214:217], v[92:95]
	v_mfma_f32_16x16x32_bf16 v[88:91], v[140:143], v[214:217], v[88:91]
	v_mfma_f32_16x16x32_bf16 v[60:63], v[132:135], v[222:225], v[60:63]
	v_mfma_f32_16x16x32_bf16 v[56:59], v[140:143], v[222:225], v[56:59]
	v_mfma_f32_16x16x32_bf16 v[28:31], v[132:135], v[230:233], v[28:31]
	v_mfma_f32_16x16x32_bf16 v[24:27], v[140:143], v[230:233], v[24:27]
	s_setprio 0
	s_setprio 1
	v_mfma_f32_16x16x32_bf16 v[108:111], v[144:147], v[202:205], 0
	v_mfma_f32_16x16x32_bf16 v[100:103], v[194:197], v[202:205], 0
	v_mfma_f32_16x16x32_bf16 v[76:79], v[144:147], v[210:213], 0
	v_mfma_f32_16x16x32_bf16 v[72:75], v[194:197], v[210:213], 0
	v_mfma_f32_16x16x32_bf16 v[44:47], v[144:147], v[218:221], 0
	v_mfma_f32_16x16x32_bf16 v[40:43], v[194:197], v[218:221], 0
	v_mfma_f32_16x16x32_bf16 v[12:15], v[144:147], v[226:229], 0
	v_mfma_f32_16x16x32_bf16 v[8:11], v[194:197], v[226:229], 0
	v_mfma_f32_16x16x32_bf16 v[108:111], v[168:171], v[206:209], v[108:111]
	v_mfma_f32_16x16x32_bf16 v[100:103], v[198:201], v[206:209], v[100:103]
	v_mfma_f32_16x16x32_bf16 v[76:79], v[168:171], v[214:217], v[76:79]
	v_mfma_f32_16x16x32_bf16 v[72:75], v[198:201], v[214:217], v[72:75]
	v_mfma_f32_16x16x32_bf16 v[44:47], v[168:171], v[222:225], v[44:47]
	v_mfma_f32_16x16x32_bf16 v[40:43], v[198:201], v[222:225], v[40:43]
	v_mfma_f32_16x16x32_bf16 v[12:15], v[168:171], v[230:233], v[12:15]
	v_mfma_f32_16x16x32_bf16 v[8:11], v[198:201], v[230:233], v[8:11]
	s_setprio 0
	s_barrier
	s_add_i32 s64, s52, s70
	v_lshl_add_u64 v[234:235], s[10:11], 0, v[152:153]
	s_mov_b32 m0, s64
	ds_read_b128 v[202:205], v188 offset:16384
	ds_read_b128 v[206:209], v188 offset:17408
	ds_read_b128 v[210:213], v188 offset:18432
	ds_read_b128 v[214:217], v188 offset:19456
	ds_read_b128 v[218:221], v188 offset:20480
	ds_read_b128 v[222:225], v188 offset:21504
	ds_read_b128 v[226:229], v188 offset:22528
	ds_read_b128 v[230:233], v188 offset:23552
	global_load_lds_dwordx4 v[234:235], off
	s_add_i32 m0, s64, 0x2000
	s_add_u32 s64, s10, 0x40000
	v_lshl_add_u64 v[236:237], s[10:11], 0, v[148:149]
	s_addc_u32 s65, s11, 0
	s_add_i32 s66, s53, s70
	global_load_lds_dwordx4 v[236:237], off
	v_lshl_add_u64 v[238:239], s[64:65], 0, v[152:153]
	s_mov_b32 m0, s66
	v_lshl_add_u64 v[240:241], s[28:29], 0, v[150:151]
	global_load_lds_dwordx4 v[238:239], off
	v_lshl_add_u64 v[238:239], s[64:65], 0, v[148:149]
	s_add_i32 m0, s66, 0x2000
	s_nop 0
	global_load_lds_dwordx4 v[238:239], off
	v_lshl_add_u64 v[238:239], s[28:29], 0, v[154:155]
	s_mov_b32 m0, s25
	s_nop 0
	global_load_lds_dwordx4 v[238:239], off
	s_mov_b32 m0, s33
	s_nop 0
	global_load_lds_dwordx4 v[240:241], off
	s_waitcnt vmcnt(8)
	s_waitcnt lgkmcnt(0)
	s_barrier
	s_setprio 1
	s_waitcnt lgkmcnt(0)
	v_mfma_f32_16x16x32_bf16 v[116:119], v[128:131], v[202:205], 0
	v_mfma_f32_16x16x32_bf16 v[112:115], v[136:139], v[202:205], 0
	v_mfma_f32_16x16x32_bf16 v[84:87], v[128:131], v[210:213], 0
	v_mfma_f32_16x16x32_bf16 v[80:83], v[136:139], v[210:213], 0
	v_mfma_f32_16x16x32_bf16 v[52:55], v[128:131], v[218:221], 0
	v_mfma_f32_16x16x32_bf16 v[48:51], v[136:139], v[218:221], 0
	v_mfma_f32_16x16x32_bf16 v[20:23], v[128:131], v[226:229], 0
	v_mfma_f32_16x16x32_bf16 v[16:19], v[136:139], v[226:229], 0
	v_mfma_f32_16x16x32_bf16 v[116:119], v[132:135], v[206:209], v[116:119]
	v_mfma_f32_16x16x32_bf16 v[112:115], v[140:143], v[206:209], v[112:115]
	v_mfma_f32_16x16x32_bf16 v[84:87], v[132:135], v[214:217], v[84:87]
	v_mfma_f32_16x16x32_bf16 v[80:83], v[140:143], v[214:217], v[80:83]
	v_mfma_f32_16x16x32_bf16 v[52:55], v[132:135], v[222:225], v[52:55]
	v_mfma_f32_16x16x32_bf16 v[48:51], v[140:143], v[222:225], v[48:51]
	v_mfma_f32_16x16x32_bf16 v[20:23], v[132:135], v[230:233], v[20:23]
	v_mfma_f32_16x16x32_bf16 v[16:19], v[140:143], v[230:233], v[16:19]
	s_setprio 0
	s_setprio 1
	v_mfma_f32_16x16x32_bf16 v[104:107], v[144:147], v[202:205], 0
	v_mfma_f32_16x16x32_bf16 v[96:99], v[194:197], v[202:205], 0
	v_mfma_f32_16x16x32_bf16 v[68:71], v[144:147], v[210:213], 0
	v_mfma_f32_16x16x32_bf16 v[64:67], v[194:197], v[210:213], 0
	v_mfma_f32_16x16x32_bf16 v[36:39], v[144:147], v[218:221], 0
	v_mfma_f32_16x16x32_bf16 v[32:35], v[194:197], v[218:221], 0
	v_mfma_f32_16x16x32_bf16 v[4:7], v[144:147], v[226:229], 0
	v_mfma_f32_16x16x32_bf16 v[0:3], v[194:197], v[226:229], 0
	v_mfma_f32_16x16x32_bf16 v[104:107], v[168:171], v[206:209], v[104:107]
	v_mfma_f32_16x16x32_bf16 v[96:99], v[198:201], v[206:209], v[96:99]
	v_mfma_f32_16x16x32_bf16 v[68:71], v[168:171], v[214:217], v[68:71]
	v_mfma_f32_16x16x32_bf16 v[64:67], v[198:201], v[214:217], v[64:67]
	v_mfma_f32_16x16x32_bf16 v[36:39], v[168:171], v[222:225], v[36:39]
	v_mfma_f32_16x16x32_bf16 v[32:35], v[198:201], v[222:225], v[32:35]
	v_mfma_f32_16x16x32_bf16 v[4:7], v[168:171], v[230:233], v[4:7]
	v_mfma_f32_16x16x32_bf16 v[0:3], v[198:201], v[230:233], v[0:3]
	s_setprio 0
	s_barrier
	s_add_i32 s64, 0, 0x18000
	s_add_i32 s65, 0, 0x1c000
	v_add_u32_e32 v140, s64, v174
	v_add_u32_e32 v165, s65, v174
	ds_read_b128 v[128:131], v140
	ds_read_b128 v[132:135], v140 offset:1024
	ds_read_b128 v[136:139], v140 offset:2048
	ds_read_b128 v[140:143], v140 offset:3072
	ds_read_b128 v[144:147], v165
	ds_read_b128 v[168:171], v165 offset:1024
	ds_read_b128 v[194:197], v165 offset:2048
	ds_read_b128 v[198:201], v165 offset:3072
	s_add_u32 s28, s28, 0x40000
	s_addc_u32 s29, s29, 0
	s_mov_b32 m0, s34
	v_lshl_add_u64 v[242:243], s[28:29], 0, v[154:155]
	ds_read_b128 v[202:205], v188 offset:32768
	ds_read_b128 v[206:209], v188 offset:33792
	ds_read_b128 v[210:213], v188 offset:34816
	ds_read_b128 v[214:217], v188 offset:35840
	ds_read_b128 v[218:221], v188 offset:36864
	ds_read_b128 v[222:225], v188 offset:37888
	ds_read_b128 v[226:229], v188 offset:38912
	ds_read_b128 v[230:233], v188 offset:39936
	global_load_lds_dwordx4 v[242:243], off
	v_lshl_add_u64 v[242:243], s[28:29], 0, v[150:151]
	s_mov_b32 m0, s35
	s_nop 0
	global_load_lds_dwordx4 v[242:243], off
	s_waitcnt vmcnt(8)
	s_waitcnt lgkmcnt(0)
	s_barrier
	s_setprio 1
	s_waitcnt lgkmcnt(0)
	v_mfma_f32_16x16x32_bf16 v[124:127], v[128:131], v[202:205], v[124:127]
	v_mfma_f32_16x16x32_bf16 v[120:123], v[136:139], v[202:205], v[120:123]
	v_mfma_f32_16x16x32_bf16 v[92:95], v[128:131], v[210:213], v[92:95]
	v_mfma_f32_16x16x32_bf16 v[88:91], v[136:139], v[210:213], v[88:91]
	v_mfma_f32_16x16x32_bf16 v[60:63], v[128:131], v[218:221], v[60:63]
	v_mfma_f32_16x16x32_bf16 v[56:59], v[136:139], v[218:221], v[56:59]
	v_mfma_f32_16x16x32_bf16 v[28:31], v[128:131], v[226:229], v[28:31]
	v_mfma_f32_16x16x32_bf16 v[24:27], v[136:139], v[226:229], v[24:27]
	v_mfma_f32_16x16x32_bf16 v[124:127], v[132:135], v[206:209], v[124:127]
	v_mfma_f32_16x16x32_bf16 v[120:123], v[140:143], v[206:209], v[120:123]
	v_mfma_f32_16x16x32_bf16 v[92:95], v[132:135], v[214:217], v[92:95]
	v_mfma_f32_16x16x32_bf16 v[88:91], v[140:143], v[214:217], v[88:91]
	v_mfma_f32_16x16x32_bf16 v[60:63], v[132:135], v[222:225], v[60:63]
	v_mfma_f32_16x16x32_bf16 v[56:59], v[140:143], v[222:225], v[56:59]
	v_mfma_f32_16x16x32_bf16 v[28:31], v[132:135], v[230:233], v[28:31]
	v_mfma_f32_16x16x32_bf16 v[24:27], v[140:143], v[230:233], v[24:27]
	s_setprio 0
	s_setprio 1
	v_mfma_f32_16x16x32_bf16 v[108:111], v[144:147], v[202:205], v[108:111]
	v_mfma_f32_16x16x32_bf16 v[100:103], v[194:197], v[202:205], v[100:103]
	v_mfma_f32_16x16x32_bf16 v[76:79], v[144:147], v[210:213], v[76:79]
	v_mfma_f32_16x16x32_bf16 v[72:75], v[194:197], v[210:213], v[72:75]
	v_mfma_f32_16x16x32_bf16 v[44:47], v[144:147], v[218:221], v[44:47]
	v_mfma_f32_16x16x32_bf16 v[40:43], v[194:197], v[218:221], v[40:43]
	v_mfma_f32_16x16x32_bf16 v[12:15], v[144:147], v[226:229], v[12:15]
	v_mfma_f32_16x16x32_bf16 v[8:11], v[194:197], v[226:229], v[8:11]
	v_mfma_f32_16x16x32_bf16 v[108:111], v[168:171], v[206:209], v[108:111]
	v_mfma_f32_16x16x32_bf16 v[100:103], v[198:201], v[206:209], v[100:103]
	v_mfma_f32_16x16x32_bf16 v[76:79], v[168:171], v[214:217], v[76:79]
	v_mfma_f32_16x16x32_bf16 v[72:75], v[198:201], v[214:217], v[72:75]
	v_mfma_f32_16x16x32_bf16 v[44:47], v[168:171], v[222:225], v[44:47]
	v_mfma_f32_16x16x32_bf16 v[40:43], v[198:201], v[222:225], v[40:43]
	v_mfma_f32_16x16x32_bf16 v[12:15], v[168:171], v[230:233], v[12:15]
	v_mfma_f32_16x16x32_bf16 v[8:11], v[198:201], v[230:233], v[8:11]
	s_setprio 0
	s_barrier
	s_add_i32 s28, s64, s70
	v_lshl_add_u64 v[234:235], v[234:235], 0, s[12:13]
	s_mov_b32 m0, s28
	ds_read_b128 v[202:205], v188 offset:49152
	ds_read_b128 v[206:209], v188 offset:50176
	ds_read_b128 v[210:213], v188 offset:51200
	ds_read_b128 v[214:217], v188 offset:52224
	ds_read_b128 v[218:221], v188 offset:53248
	ds_read_b128 v[222:225], v188 offset:54272
	ds_read_b128 v[226:229], v188 offset:55296
	ds_read_b128 v[230:233], v188 offset:56320
	global_load_lds_dwordx4 v[234:235], off
	s_add_i32 m0, s28, 0x2000
	s_add_u32 s10, s10, 0x40080
	v_lshl_add_u64 v[234:235], v[236:237], 0, s[12:13]
	s_addc_u32 s11, s11, 0
	s_add_i32 s28, s65, s70
	global_load_lds_dwordx4 v[234:235], off
	v_lshl_add_u64 v[234:235], s[10:11], 0, v[152:153]
	s_mov_b32 m0, s28
	s_nop 0
	global_load_lds_dwordx4 v[234:235], off
	v_lshl_add_u64 v[234:235], s[10:11], 0, v[148:149]
	s_add_i32 m0, s28, 0x2000
	s_nop 0
	global_load_lds_dwordx4 v[234:235], off
	v_lshl_add_u64 v[234:235], v[238:239], 0, s[12:13]
	s_mov_b32 m0, s36
	s_nop 0
	global_load_lds_dwordx4 v[234:235], off
	v_lshl_add_u64 v[234:235], v[240:241], 0, s[12:13]
	s_mov_b32 m0, s37
	s_nop 0
	global_load_lds_dwordx4 v[234:235], off
	s_waitcnt vmcnt(8)
	s_waitcnt lgkmcnt(0)
	s_barrier
	s_setprio 1
	s_waitcnt lgkmcnt(0)
	v_mfma_f32_16x16x32_bf16 v[116:119], v[128:131], v[202:205], v[116:119]
	v_mfma_f32_16x16x32_bf16 v[112:115], v[136:139], v[202:205], v[112:115]
	v_mfma_f32_16x16x32_bf16 v[84:87], v[128:131], v[210:213], v[84:87]
	v_mfma_f32_16x16x32_bf16 v[80:83], v[136:139], v[210:213], v[80:83]
	v_mfma_f32_16x16x32_bf16 v[52:55], v[128:131], v[218:221], v[52:55]
	v_mfma_f32_16x16x32_bf16 v[48:51], v[136:139], v[218:221], v[48:51]
	v_mfma_f32_16x16x32_bf16 v[20:23], v[128:131], v[226:229], v[20:23]
	v_mfma_f32_16x16x32_bf16 v[16:19], v[136:139], v[226:229], v[16:19]
	v_mfma_f32_16x16x32_bf16 v[116:119], v[132:135], v[206:209], v[116:119]
	v_mfma_f32_16x16x32_bf16 v[112:115], v[140:143], v[206:209], v[112:115]
	v_mfma_f32_16x16x32_bf16 v[84:87], v[132:135], v[214:217], v[84:87]
	v_mfma_f32_16x16x32_bf16 v[80:83], v[140:143], v[214:217], v[80:83]
	v_mfma_f32_16x16x32_bf16 v[52:55], v[132:135], v[222:225], v[52:55]
	v_mfma_f32_16x16x32_bf16 v[48:51], v[140:143], v[222:225], v[48:51]
	v_mfma_f32_16x16x32_bf16 v[20:23], v[132:135], v[230:233], v[20:23]
	v_mfma_f32_16x16x32_bf16 v[16:19], v[140:143], v[230:233], v[16:19]
	s_setprio 0
	s_setprio 1
	v_mfma_f32_16x16x32_bf16 v[104:107], v[144:147], v[202:205], v[104:107]
	v_mfma_f32_16x16x32_bf16 v[96:99], v[194:197], v[202:205], v[96:99]
	v_mfma_f32_16x16x32_bf16 v[68:71], v[144:147], v[210:213], v[68:71]
	v_mfma_f32_16x16x32_bf16 v[64:67], v[194:197], v[210:213], v[64:67]
	v_mfma_f32_16x16x32_bf16 v[36:39], v[144:147], v[218:221], v[36:39]
	v_mfma_f32_16x16x32_bf16 v[32:35], v[194:197], v[218:221], v[32:35]
	v_mfma_f32_16x16x32_bf16 v[4:7], v[144:147], v[226:229], v[4:7]
	v_mfma_f32_16x16x32_bf16 v[0:3], v[194:197], v[226:229], v[0:3]
	v_mfma_f32_16x16x32_bf16 v[104:107], v[168:171], v[206:209], v[104:107]
	v_mfma_f32_16x16x32_bf16 v[96:99], v[198:201], v[206:209], v[96:99]
	v_mfma_f32_16x16x32_bf16 v[68:71], v[168:171], v[214:217], v[68:71]
	v_mfma_f32_16x16x32_bf16 v[64:67], v[198:201], v[214:217], v[64:67]
	v_mfma_f32_16x16x32_bf16 v[36:39], v[168:171], v[222:225], v[36:39]
	v_mfma_f32_16x16x32_bf16 v[32:35], v[198:201], v[222:225], v[32:35]
	v_mfma_f32_16x16x32_bf16 v[4:7], v[168:171], v[230:233], v[4:7]
	v_mfma_f32_16x16x32_bf16 v[0:3], v[198:201], v[230:233], v[0:3]
	s_setprio 0
	s_barrier
	s_add_i32 s63, s63, 2
	s_add_u32 s26, s26, 0x100
	s_addc_u32 s27, s27, 0
	s_add_u32 s61, s61, 0x100
	s_addc_u32 s62, s62, 0
	s_cmp_gt_u32 s63, 13

.LBB0_379:
	s_cmpk_lt_i32 s67, 0x200
	s_cselect_b64 s[0:1], -1, 0
	v_writelane_b32 v254, s0, 62
	s_and_b64 vcc, exec, s[0:1]
	s_waitcnt lgkmcnt(0)
	v_writelane_b32 v254, s1, 63
	s_barrier
	v_mbcnt_lo_u32_b32 v0, -1, 0
	v_mbcnt_hi_u32_b32 v0, -1, v0
	v_lshlrev_b32_e32 v199, 2, v0
	v_readlane_b32 s100, v254, 18
	v_readlane_b32 s101, v254, 19
	s_nop 4
	global_load_dword v200, v199, s[100:101]
	global_load_dword v201, v199, s[100:101] offset:256
	global_load_dword v202, v199, s[100:101] offset:512
	global_load_dword v203, v199, s[100:101] offset:768
	v_readlane_b32 s100, v254, 14
	v_readlane_b32 s101, v254, 15
	s_nop 4
	global_load_dword v204, v199, s[100:101]
	v_readlane_b32 s100, v254, 16
	v_readlane_b32 s101, v254, 17
	s_nop 4
	global_load_dword v205, v199, s[100:101]
	s_cbranch_vccnz .LBB0_381
	v_readlane_b32 s0, v254, 25
	s_lshl_b32 s12, s0, 4
	s_cbranch_execz .LBB0_382
	s_waitcnt vmcnt(0)
	s_branch .LBB0_384

.LBB0_384:
	v_readlane_b32 s16, v254, 6
	v_readlane_b32 s17, v254, 7
	v_readlane_b32 s18, v254, 8
	v_readlane_b32 s19, v254, 9
	v_readlane_b32 s20, v254, 10
	v_readlane_b32 s21, v254, 11
	v_readlane_b32 s22, v254, 12
	v_readlane_b32 s23, v254, 13
	v_readlane_b32 s24, v254, 14
	v_readlane_b32 s25, v254, 15
	v_mbcnt_lo_u32_b32 v0, -1, 0
	v_mbcnt_hi_u32_b32 v0, -1, v0
	v_readlane_b32 s26, v254, 16
	v_ashrrev_i32_e32 v1, 31, v0
	v_readlane_b32 s27, v254, 17
	v_readlane_b32 s28, v254, 18
	v_readlane_b32 s29, v254, 19
	v_readlane_b32 s30, v254, 20
	v_readlane_b32 s31, v254, 21
	s_mov_b64 s[16:17], s[24:25]
	v_lshlrev_b64 v[0:1], 2, v[0:1]
	s_mov_b64 s[20:21], s[28:29]
	v_lshl_add_u64 v[2:3], s[20:21], 0, v[0:1]
	s_mov_b64 s[18:19], s[26:27]
	v_mov_b32_e32 v4, v200
	v_mov_b32_e32 v5, v201
	v_mov_b32_e32 v6, v202
	v_mov_b32_e32 v7, v203
	v_lshl_add_u64 v[2:3], s[16:17], 0, v[0:1]
	v_mov_b32_e32 v2, v204
	v_lshl_add_u64 v[0:1], s[18:19], 0, v[0:1]
	v_mov_b32_e32 v0, v205
	s_add_u32 s0, s74, 0xc600000
	v_writelane_b32 v255, s72, 0
	s_mov_b32 s1, 0xc2ce8ed0
	s_mov_b32 s2, 0x42b17218
	v_writelane_b32 v255, s73, 1
	v_writelane_b32 v255, s68, 2
	s_addc_u32 s3, s75, 0
	v_mov_b32_e32 v3, 0x7f800000
	v_writelane_b32 v255, s69, 3
	v_writelane_b32 v255, s0, 4
	s_mov_b32 s0, 0x3fb8aa3b
	v_writelane_b32 v255, s3, 5
	s_add_u32 s3, s74, 0xf900000
	v_writelane_b32 v255, s3, 6
	s_addc_u32 s3, s75, 0
	v_writelane_b32 v255, s3, 7
	s_add_u32 s3, s74, 0xfa04000
	v_writelane_b32 v255, s3, 8
	s_addc_u32 s3, s75, 0
	v_mov_b32_e32 v8, 0x3e4ccccd
	s_cmpk_lt_i32 s67, 0x100
	v_writelane_b32 v255, s3, 9
	v_writelane_b32 v255, s67, 10
	s_mov_b64 s[22:23], s[30:31]
	s_mov_b32 s9, 0
	v_mov_b32_e32 v1, 0
	s_mov_b64 s[4:5], -1
	s_movk_i32 s80, 0x1400
	s_mov_b64 s[34:35], 0x1000
	s_movk_i32 s81, 0xa00
	s_mov_b64 s[22:23], 0x100
	s_mov_b64 s[24:25], 0xa0000
	v_mov_b32_e32 v234, 0x358637bd
	s_waitcnt vmcnt(4)
	v_mul_f32_e32 v9, v4, v5
	ds_swizzle_b32 v9, v9 offset:swizzle(SWAP,1)
	s_waitcnt vmcnt(2)
	v_mul_f32_e32 v10, v6, v7
	ds_swizzle_b32 v10, v10 offset:swizzle(SWAP,1)
	s_waitcnt vmcnt(1)
	v_and_b32_e32 v11, 0x7fffffff, v2
	ds_swizzle_b32 v11, v11 offset:swizzle(SWAP,1)
	s_waitcnt vmcnt(0)
	v_and_b32_e32 v12, 0x7fffffff, v0
	ds_swizzle_b32 v12, v12 offset:swizzle(SWAP,1)
	s_waitcnt lgkmcnt(3)
	v_fmac_f32_e32 v9, v4, v5
	v_max_f32_e64 v2, |v2|, |v2|
	s_waitcnt lgkmcnt(2)
	v_fmac_f32_e32 v10, v6, v7
	s_waitcnt lgkmcnt(1)
	v_max_f32_e32 v4, v11, v11
	ds_swizzle_b32 v6, v9 offset:swizzle(SWAP,2)
	v_max_f32_e64 v0, |v0|, |v0|
	s_waitcnt lgkmcnt(1)
	v_max_f32_e32 v5, v12, v12
	ds_swizzle_b32 v7, v10 offset:swizzle(SWAP,2)
	v_max_f32_e32 v2, v2, v4
	v_max_f32_e32 v0, v0, v5
	ds_swizzle_b32 v4, v2 offset:swizzle(SWAP,2)
	ds_swizzle_b32 v5, v0 offset:swizzle(SWAP,2)
	s_waitcnt lgkmcnt(3)
	v_add_f32_e32 v6, v9, v6
	s_waitcnt lgkmcnt(2)
	v_add_f32_e32 v7, v10, v7
	ds_swizzle_b32 v9, v6 offset:swizzle(SWAP,4)
	ds_swizzle_b32 v10, v7 offset:swizzle(SWAP,4)
	s_waitcnt lgkmcnt(3)
	v_max_f32_e32 v4, v4, v4
	s_waitcnt lgkmcnt(2)
	v_max_f32_e32 v5, v5, v5
	v_max_f32_e32 v2, v2, v4
	v_max_f32_e32 v0, v0, v5
	ds_swizzle_b32 v4, v2 offset:swizzle(SWAP,4)
	ds_swizzle_b32 v5, v0 offset:swizzle(SWAP,4)
	s_waitcnt lgkmcnt(3)
	v_add_f32_e32 v6, v6, v9
	s_waitcnt lgkmcnt(2)
	v_add_f32_e32 v7, v7, v10
	ds_swizzle_b32 v9, v6 offset:swizzle(SWAP,8)
	ds_swizzle_b32 v10, v7 offset:swizzle(SWAP,8)
	s_waitcnt lgkmcnt(3)
	v_max_f32_e32 v4, v4, v4
	s_waitcnt lgkmcnt(2)
	v_max_f32_e32 v5, v5, v5
	v_max_f32_e32 v2, v2, v4
	v_max_f32_e32 v0, v0, v5
	ds_swizzle_b32 v4, v2 offset:swizzle(SWAP,8)
	ds_swizzle_b32 v5, v0 offset:swizzle(SWAP,8)
	s_waitcnt lgkmcnt(3)
	v_add_f32_e32 v6, v6, v9
	s_waitcnt lgkmcnt(2)
	v_add_f32_e32 v7, v7, v10
	ds_swizzle_b32 v9, v6 offset:swizzle(SWAP,16)
	ds_swizzle_b32 v10, v7 offset:swizzle(SWAP,16)
	s_waitcnt lgkmcnt(3)
	v_max_f32_e32 v4, v4, v4
	s_waitcnt lgkmcnt(2)
	v_max_f32_e32 v5, v5, v5
	v_max_f32_e32 v2, v2, v4
	v_max_f32_e32 v0, v0, v5
	ds_swizzle_b32 v4, v2 offset:swizzle(SWAP,16)
	s_waitcnt lgkmcnt(2)
	v_add_f32_e32 v6, v6, v9
	ds_swizzle_b32 v5, v0 offset:swizzle(SWAP,16)
	s_waitcnt lgkmcnt(2)
	v_add_f32_e32 v7, v7, v10
	v_mov_b32_e32 v9, v6
	v_mov_b32_e32 v10, v7
	s_nop 0
	v_permlane32_swap_b32_e32 v6, v9
	v_permlane32_swap_b32_e32 v7, v10
	v_add_f32_e32 v6, v6, v9
	v_add_f32_e32 v7, v7, v10
	v_mul_f32_e32 v9, 0x3fb8aa3b, v6
	v_mul_f32_e32 v10, 0x3fb8aa3b, v7
	s_waitcnt lgkmcnt(1)
	v_max_f32_e32 v4, v4, v4
	v_fma_f32 v11, v6, s0, -v9
	v_rndne_f32_e32 v12, v9
	s_waitcnt lgkmcnt(0)
	v_max_f32_e32 v5, v5, v5
	v_fma_f32 v13, v7, s0, -v10
	v_rndne_f32_e32 v14, v10
	v_max_f32_e32 v2, v2, v4
	v_fmac_f32_e32 v11, 0x32a5705f, v6
	v_sub_f32_e32 v4, v9, v12
	v_max_f32_e32 v0, v0, v5
	v_fmac_f32_e32 v13, 0x32a5705f, v7
	v_sub_f32_e32 v9, v10, v14
	v_add_f32_e32 v4, v4, v11
	v_cvt_i32_f32_e32 v5, v12
	v_cvt_i32_f32_e32 v10, v14
	v_mov_b32_e32 v12, v2
	v_mov_b32_e32 v14, v0
	v_add_f32_e32 v9, v9, v13
	v_exp_f32_e32 v4, v4
	v_permlane32_swap_b32_e32 v2, v12
	v_permlane32_swap_b32_e32 v0, v14
	v_exp_f32_e32 v9, v9
	v_max_f32_e32 v11, v12, v12
	v_max_f32_e32 v2, v2, v2
	v_max_f32_e32 v12, v14, v14
	v_max_f32_e32 v0, v0, v0
	v_max_f32_e32 v2, v2, v11
	v_max_f32_e32 v0, v0, v12
	v_mul_f32_e32 v0, v2, v0
	v_ldexp_f32 v2, v4, v5
	v_cmp_ngt_f32_e32 vcc, s1, v6
	v_ldexp_f32 v4, v9, v10
	v_mul_f32_e32 v0, 0x42800000, v0
	v_cndmask_b32_e32 v2, 0, v2, vcc
	v_cmp_ngt_f32_e32 vcc, s1, v7
	v_readlane_b32 s1, v254, 25
	s_mul_i32 s57, s1, 0xa000
	v_cndmask_b32_e32 v4, 0, v4, vcc
	v_cmp_nlt_f32_e32 vcc, s2, v6
	s_nop 1
	v_cndmask_b32_e32 v2, v3, v2, vcc
	v_cmp_nlt_f32_e32 vcc, s2, v7
	s_cselect_b64 s[2:3], -1, 0
	s_lshl_b32 s36, s1, 18
	v_cndmask_b32_e32 v3, v3, v4, vcc
	v_sub_f32_e32 v2, v2, v3
	s_or_b32 s54, s36, 0x10000
	v_readfirstlane_b32 s0, v2
	v_mov_b32_e32 v2, 0xc2700000
	v_fmac_f32_e32 v2, 0x3e38aa3b, v0
	v_add_f32_e32 v232, s0, v8
	s_lshl_b32 s0, s1, 12
	s_add_i32 s41, s0, 0
	s_lshl_b32 s0, s1, 13
	s_add_i32 s16, s0, 0
	s_add_i32 s0, s57, 0x7800
	v_writelane_b32 v255, s0, 11
	v_writelane_b32 v255, s2, 12
	s_mov_b32 s0, 0
	v_max_f32_e32 v0, 0, v2
	v_writelane_b32 v255, s3, 13
	v_writelane_b32 v255, s0, 14
	v_readfirstlane_b32 s40, v0
	v_writelane_b32 v255, s78, 15
	s_or_b32 s55, s36, 0x20000
	v_cmp_neq_f32_e64 s[52:53], s40, 0
	s_or_b32 s56, s36, 0x30000
	s_add_i32 s58, s57, 0x2800
	s_add_i32 s59, s57, 0x5000
	v_cndmask_b32_e64 v233, 0, 1, s[2:3]
	s_add_i32 s19, s41, 0x8000
	s_add_i32 s43, s41, 0x400
	s_add_i32 s37, s41, 0x8400
	s_add_i32 s38, s41, 0x800
	s_add_i32 s39, s41, 0x8800
	s_add_i32 s42, s41, 0xc00
	s_add_i32 s66, s41, 0x8c00
	v_writelane_b32 v255, s79, 16
	s_branch .LBB0_386

.LBB0_673:
	s_ashr_i32 s17, s16, 31
	s_lshl_b64 s[18:19], s[16:17], 19
	v_readlane_b32 s15, v255, 4
	s_add_u32 s18, s15, s18
	v_readlane_b32 s15, v255, 5
	s_addc_u32 s19, s15, s19
	s_and_b64 s[22:23], s[8:9], exec
	s_cselect_b32 s17, s19, s21
	s_cselect_b32 s41, s18, s20
	s_ashr_i32 s15, s14, 31
	s_lshl_b64 s[22:23], s[14:15], 19
	s_add_u32 s22, s2, s22
	s_addc_u32 s23, s3, s23
	s_and_b64 s[28:29], s[8:9], exec
	s_cselect_b32 s15, s23, s11
	s_cselect_b32 s42, s22, s10
	s_add_u32 s28, s20, 0x40080
	s_addc_u32 s29, s21, 0
	s_add_u32 s43, s10, 0x100
	s_nop 7
	s_nop 7
	v_readlane_b32 s49, v254, 54
	s_addc_u32 s44, s11, 0
	s_mov_b32 s45, -2
	ds_read_b128 v[128:131], v207
	ds_read_b128 v[132:135], v207 offset:1024
	ds_read_b128 v[136:139], v207 offset:2048
	ds_read_b128 v[140:143], v207 offset:3072
	ds_read_b128 v[144:147], v208
	ds_read_b128 v[148:151], v208 offset:1024
	ds_read_b128 v[152:155], v208 offset:2048
	ds_read_b128 v[156:159], v208 offset:3072
	s_add_u32 s10, s28, 0xfffc0080
	s_addc_u32 s11, s29, -1
	s_cmp_eq_u32 s45, 12
	s_cselect_b32 s21, s17, s11
	s_cselect_b32 s20, s41, s10
	s_cselect_b32 s11, s15, s44
	s_cselect_b32 s10, s42, s43
	v_lshl_add_u64 v[214:215], s[28:29], 0, v[184:185]
	s_add_i32 m0, s25, 0xc000
	ds_read_b128 v[160:163], v209
	ds_read_b128 v[164:167], v209 offset:1024
	ds_read_b128 v[168:171], v209 offset:2048
	ds_read_b128 v[172:175], v209 offset:3072
	ds_read_b128 v[192:195], v209 offset:4096
	ds_read_b128 v[196:199], v209 offset:5120
	ds_read_b128 v[200:203], v209 offset:6144
	ds_read_b128 v[210:213], v209 offset:7168
	global_load_lds_dwordx4 v[214:215], off
	v_lshl_add_u64 v[214:215], s[28:29], 0, v[186:187]
	s_add_i32 m0, s25, 0xe000
	s_nop 0
	global_load_lds_dwordx4 v[214:215], off
	s_waitcnt vmcnt(8)
	s_waitcnt lgkmcnt(0)
	s_barrier
	s_setprio 1
	s_waitcnt lgkmcnt(0)
	v_mfma_f32_16x16x32_bf16 v[124:127], v[128:131], v[160:163], 0
	v_mfma_f32_16x16x32_bf16 v[120:123], v[136:139], v[160:163], 0
	v_mfma_f32_16x16x32_bf16 v[108:111], v[128:131], v[168:171], 0
	v_mfma_f32_16x16x32_bf16 v[104:107], v[136:139], v[168:171], 0
	v_mfma_f32_16x16x32_bf16 v[92:95], v[128:131], v[192:195], 0
	v_mfma_f32_16x16x32_bf16 v[88:91], v[136:139], v[192:195], 0
	v_mfma_f32_16x16x32_bf16 v[76:79], v[128:131], v[200:203], 0
	v_mfma_f32_16x16x32_bf16 v[72:75], v[136:139], v[200:203], 0
	v_mfma_f32_16x16x32_bf16 v[124:127], v[132:135], v[164:167], v[124:127]
	v_mfma_f32_16x16x32_bf16 v[120:123], v[140:143], v[164:167], v[120:123]
	v_mfma_f32_16x16x32_bf16 v[108:111], v[132:135], v[172:175], v[108:111]
	v_mfma_f32_16x16x32_bf16 v[104:107], v[140:143], v[172:175], v[104:107]
	v_mfma_f32_16x16x32_bf16 v[92:95], v[132:135], v[196:199], v[92:95]
	v_mfma_f32_16x16x32_bf16 v[88:91], v[140:143], v[196:199], v[88:91]
	v_mfma_f32_16x16x32_bf16 v[76:79], v[132:135], v[210:213], v[76:79]
	v_mfma_f32_16x16x32_bf16 v[72:75], v[140:143], v[210:213], v[72:75]
	s_setprio 0
	s_setprio 1
	v_mfma_f32_16x16x32_bf16 v[116:119], v[144:147], v[160:163], 0
	v_mfma_f32_16x16x32_bf16 v[112:115], v[152:155], v[160:163], 0
	v_mfma_f32_16x16x32_bf16 v[100:103], v[144:147], v[168:171], 0
	v_mfma_f32_16x16x32_bf16 v[96:99], v[152:155], v[168:171], 0
	v_mfma_f32_16x16x32_bf16 v[84:87], v[144:147], v[192:195], 0
	v_mfma_f32_16x16x32_bf16 v[80:83], v[152:155], v[192:195], 0
	v_mfma_f32_16x16x32_bf16 v[68:71], v[144:147], v[200:203], 0
	v_mfma_f32_16x16x32_bf16 v[64:67], v[152:155], v[200:203], 0
	v_mfma_f32_16x16x32_bf16 v[116:119], v[148:151], v[164:167], v[116:119]
	v_mfma_f32_16x16x32_bf16 v[112:115], v[156:159], v[164:167], v[112:115]
	v_mfma_f32_16x16x32_bf16 v[100:103], v[148:151], v[172:175], v[100:103]
	v_mfma_f32_16x16x32_bf16 v[96:99], v[156:159], v[172:175], v[96:99]
	v_mfma_f32_16x16x32_bf16 v[84:87], v[148:151], v[196:199], v[84:87]
	v_mfma_f32_16x16x32_bf16 v[80:83], v[156:159], v[196:199], v[80:83]
	v_mfma_f32_16x16x32_bf16 v[68:71], v[148:151], v[210:213], v[68:71]
	v_mfma_f32_16x16x32_bf16 v[64:67], v[156:159], v[210:213], v[64:67]
	s_setprio 0
	s_barrier
	s_add_i32 s46, s39, s49
	v_lshl_add_u64 v[214:215], s[10:11], 0, v[178:179]
	s_mov_b32 m0, s46
	ds_read_b128 v[160:163], v209 offset:16384
	ds_read_b128 v[164:167], v209 offset:17408
	ds_read_b128 v[168:171], v209 offset:18432
	ds_read_b128 v[172:175], v209 offset:19456
	ds_read_b128 v[192:195], v209 offset:20480
	ds_read_b128 v[196:199], v209 offset:21504
	ds_read_b128 v[200:203], v209 offset:22528
	ds_read_b128 v[210:213], v209 offset:23552
	global_load_lds_dwordx4 v[214:215], off
	s_add_i32 m0, s46, 0x2000
	s_add_u32 s46, s10, 0x40000
	v_lshl_add_u64 v[216:217], s[10:11], 0, v[182:183]
	s_addc_u32 s47, s11, 0
	s_add_i32 s48, s40, s49
	global_load_lds_dwordx4 v[216:217], off
	v_lshl_add_u64 v[218:219], s[46:47], 0, v[178:179]
	s_mov_b32 m0, s48
	v_lshl_add_u64 v[220:221], s[20:21], 0, v[180:181]
	global_load_lds_dwordx4 v[218:219], off
	v_lshl_add_u64 v[218:219], s[46:47], 0, v[182:183]
	s_add_i32 m0, s48, 0x2000
	s_nop 0
	global_load_lds_dwordx4 v[218:219], off
	v_lshl_add_u64 v[218:219], s[20:21], 0, v[176:177]
	s_mov_b32 m0, s25
	s_nop 0
	global_load_lds_dwordx4 v[218:219], off
	s_mov_b32 m0, s27
	s_nop 0
	global_load_lds_dwordx4 v[220:221], off
	s_waitcnt vmcnt(8)
	s_waitcnt lgkmcnt(0)
	s_barrier
	s_setprio 1
	s_waitcnt lgkmcnt(0)
	v_mfma_f32_16x16x32_bf16 v[60:63], v[128:131], v[160:163], 0
	v_mfma_f32_16x16x32_bf16 v[56:59], v[136:139], v[160:163], 0
	v_mfma_f32_16x16x32_bf16 v[44:47], v[128:131], v[168:171], 0
	v_mfma_f32_16x16x32_bf16 v[40:43], v[136:139], v[168:171], 0
	v_mfma_f32_16x16x32_bf16 v[28:31], v[128:131], v[192:195], 0
	v_mfma_f32_16x16x32_bf16 v[24:27], v[136:139], v[192:195], 0
	v_mfma_f32_16x16x32_bf16 v[12:15], v[128:131], v[200:203], 0
	v_mfma_f32_16x16x32_bf16 v[8:11], v[136:139], v[200:203], 0
	v_mfma_f32_16x16x32_bf16 v[60:63], v[132:135], v[164:167], v[60:63]
	v_mfma_f32_16x16x32_bf16 v[56:59], v[140:143], v[164:167], v[56:59]
	v_mfma_f32_16x16x32_bf16 v[44:47], v[132:135], v[172:175], v[44:47]
	v_mfma_f32_16x16x32_bf16 v[40:43], v[140:143], v[172:175], v[40:43]
	v_mfma_f32_16x16x32_bf16 v[28:31], v[132:135], v[196:199], v[28:31]
	v_mfma_f32_16x16x32_bf16 v[24:27], v[140:143], v[196:199], v[24:27]
	v_mfma_f32_16x16x32_bf16 v[12:15], v[132:135], v[210:213], v[12:15]
	v_mfma_f32_16x16x32_bf16 v[8:11], v[140:143], v[210:213], v[8:11]
	s_setprio 0
	s_setprio 1
	v_mfma_f32_16x16x32_bf16 v[52:55], v[144:147], v[160:163], 0
	v_mfma_f32_16x16x32_bf16 v[48:51], v[152:155], v[160:163], 0
	v_mfma_f32_16x16x32_bf16 v[36:39], v[144:147], v[168:171], 0
	v_mfma_f32_16x16x32_bf16 v[32:35], v[152:155], v[168:171], 0
	v_mfma_f32_16x16x32_bf16 v[20:23], v[144:147], v[192:195], 0
	v_mfma_f32_16x16x32_bf16 v[16:19], v[152:155], v[192:195], 0
	v_mfma_f32_16x16x32_bf16 v[4:7], v[144:147], v[200:203], 0
	v_mfma_f32_16x16x32_bf16 v[0:3], v[152:155], v[200:203], 0
	v_mfma_f32_16x16x32_bf16 v[52:55], v[148:151], v[164:167], v[52:55]
	v_mfma_f32_16x16x32_bf16 v[48:51], v[156:159], v[164:167], v[48:51]
	v_mfma_f32_16x16x32_bf16 v[36:39], v[148:151], v[172:175], v[36:39]
	v_mfma_f32_16x16x32_bf16 v[32:35], v[156:159], v[172:175], v[32:35]
	v_mfma_f32_16x16x32_bf16 v[20:23], v[148:151], v[196:199], v[20:23]
	v_mfma_f32_16x16x32_bf16 v[16:19], v[156:159], v[196:199], v[16:19]
	v_mfma_f32_16x16x32_bf16 v[4:7], v[148:151], v[210:213], v[4:7]
	v_mfma_f32_16x16x32_bf16 v[0:3], v[156:159], v[210:213], v[0:3]
	s_setprio 0
	s_barrier
	s_add_i32 s46, 0, 0x18000
	s_add_i32 s47, 0, 0x1c000
	v_add_u32_e32 v140, s46, v205
	v_add_u32_e32 v156, s47, v205
	ds_read_b128 v[128:131], v140
	ds_read_b128 v[132:135], v140 offset:1024
	ds_read_b128 v[136:139], v140 offset:2048
	ds_read_b128 v[140:143], v140 offset:3072
	ds_read_b128 v[144:147], v156
	ds_read_b128 v[148:151], v156 offset:1024
	ds_read_b128 v[152:155], v156 offset:2048
	ds_read_b128 v[156:159], v156 offset:3072
	s_add_u32 s20, s20, 0x40000
	s_addc_u32 s21, s21, 0
	s_mov_b32 m0, s30
	v_lshl_add_u64 v[222:223], s[20:21], 0, v[176:177]
	ds_read_b128 v[160:163], v209 offset:32768
	ds_read_b128 v[164:167], v209 offset:33792
	ds_read_b128 v[168:171], v209 offset:34816
	ds_read_b128 v[172:175], v209 offset:35840
	ds_read_b128 v[192:195], v209 offset:36864
	ds_read_b128 v[196:199], v209 offset:37888
	ds_read_b128 v[200:203], v209 offset:38912
	ds_read_b128 v[210:213], v209 offset:39936
	global_load_lds_dwordx4 v[222:223], off
	v_lshl_add_u64 v[222:223], s[20:21], 0, v[180:181]
	s_mov_b32 m0, s31
	s_nop 0
	global_load_lds_dwordx4 v[222:223], off
	s_waitcnt vmcnt(8)
	s_waitcnt lgkmcnt(0)
	s_barrier
	s_setprio 1
	s_waitcnt lgkmcnt(0)
	v_mfma_f32_16x16x32_bf16 v[124:127], v[128:131], v[160:163], v[124:127]
	v_mfma_f32_16x16x32_bf16 v[120:123], v[136:139], v[160:163], v[120:123]
	v_mfma_f32_16x16x32_bf16 v[108:111], v[128:131], v[168:171], v[108:111]
	v_mfma_f32_16x16x32_bf16 v[104:107], v[136:139], v[168:171], v[104:107]
	v_mfma_f32_16x16x32_bf16 v[92:95], v[128:131], v[192:195], v[92:95]
	v_mfma_f32_16x16x32_bf16 v[88:91], v[136:139], v[192:195], v[88:91]
	v_mfma_f32_16x16x32_bf16 v[76:79], v[128:131], v[200:203], v[76:79]
	v_mfma_f32_16x16x32_bf16 v[72:75], v[136:139], v[200:203], v[72:75]
	v_mfma_f32_16x16x32_bf16 v[124:127], v[132:135], v[164:167], v[124:127]
	v_mfma_f32_16x16x32_bf16 v[120:123], v[140:143], v[164:167], v[120:123]
	v_mfma_f32_16x16x32_bf16 v[108:111], v[132:135], v[172:175], v[108:111]
	v_mfma_f32_16x16x32_bf16 v[104:107], v[140:143], v[172:175], v[104:107]
	v_mfma_f32_16x16x32_bf16 v[92:95], v[132:135], v[196:199], v[92:95]
	v_mfma_f32_16x16x32_bf16 v[88:91], v[140:143], v[196:199], v[88:91]
	v_mfma_f32_16x16x32_bf16 v[76:79], v[132:135], v[210:213], v[76:79]
	v_mfma_f32_16x16x32_bf16 v[72:75], v[140:143], v[210:213], v[72:75]
	s_setprio 0
	s_setprio 1
	v_mfma_f32_16x16x32_bf16 v[116:119], v[144:147], v[160:163], v[116:119]
	v_mfma_f32_16x16x32_bf16 v[112:115], v[152:155], v[160:163], v[112:115]
	v_mfma_f32_16x16x32_bf16 v[100:103], v[144:147], v[168:171], v[100:103]
	v_mfma_f32_16x16x32_bf16 v[96:99], v[152:155], v[168:171], v[96:99]
	v_mfma_f32_16x16x32_bf16 v[84:87], v[144:147], v[192:195], v[84:87]
	v_mfma_f32_16x16x32_bf16 v[80:83], v[152:155], v[192:195], v[80:83]
	v_mfma_f32_16x16x32_bf16 v[68:71], v[144:147], v[200:203], v[68:71]
	v_mfma_f32_16x16x32_bf16 v[64:67], v[152:155], v[200:203], v[64:67]
	v_mfma_f32_16x16x32_bf16 v[116:119], v[148:151], v[164:167], v[116:119]
	v_mfma_f32_16x16x32_bf16 v[112:115], v[156:159], v[164:167], v[112:115]
	v_mfma_f32_16x16x32_bf16 v[100:103], v[148:151], v[172:175], v[100:103]
	v_mfma_f32_16x16x32_bf16 v[96:99], v[156:159], v[172:175], v[96:99]
	v_mfma_f32_16x16x32_bf16 v[84:87], v[148:151], v[196:199], v[84:87]
	v_mfma_f32_16x16x32_bf16 v[80:83], v[156:159], v[196:199], v[80:83]
	v_mfma_f32_16x16x32_bf16 v[68:71], v[148:151], v[210:213], v[68:71]
	v_mfma_f32_16x16x32_bf16 v[64:67], v[156:159], v[210:213], v[64:67]
	s_setprio 0
	s_barrier
	s_add_i32 s20, s46, s49
	v_lshl_add_u64 v[214:215], v[214:215], 0, s[12:13]
	s_mov_b32 m0, s20
	ds_read_b128 v[160:163], v209 offset:49152
	ds_read_b128 v[164:167], v209 offset:50176
	ds_read_b128 v[168:171], v209 offset:51200
	ds_read_b128 v[172:175], v209 offset:52224
	ds_read_b128 v[192:195], v209 offset:53248
	ds_read_b128 v[196:199], v209 offset:54272
	ds_read_b128 v[200:203], v209 offset:55296
	ds_read_b128 v[210:213], v209 offset:56320
	global_load_lds_dwordx4 v[214:215], off
	s_add_i32 m0, s20, 0x2000
	s_add_u32 s10, s10, 0x40080
	v_lshl_add_u64 v[214:215], v[216:217], 0, s[12:13]
	s_addc_u32 s11, s11, 0
	s_add_i32 s20, s47, s49
	global_load_lds_dwordx4 v[214:215], off
	v_lshl_add_u64 v[214:215], s[10:11], 0, v[178:179]
	s_mov_b32 m0, s20
	s_nop 0
	global_load_lds_dwordx4 v[214:215], off
	v_lshl_add_u64 v[214:215], s[10:11], 0, v[182:183]
	s_add_i32 m0, s20, 0x2000
	s_nop 0
	global_load_lds_dwordx4 v[214:215], off
	v_lshl_add_u64 v[214:215], v[218:219], 0, s[12:13]
	s_mov_b32 m0, s34
	s_nop 0
	global_load_lds_dwordx4 v[214:215], off
	v_lshl_add_u64 v[214:215], v[220:221], 0, s[12:13]
	s_mov_b32 m0, s35
	s_nop 0
	global_load_lds_dwordx4 v[214:215], off
	s_waitcnt vmcnt(8)
	s_waitcnt lgkmcnt(0)
	s_barrier
	s_setprio 1
	s_waitcnt lgkmcnt(0)
	v_mfma_f32_16x16x32_bf16 v[60:63], v[128:131], v[160:163], v[60:63]
	v_mfma_f32_16x16x32_bf16 v[56:59], v[136:139], v[160:163], v[56:59]
	v_mfma_f32_16x16x32_bf16 v[44:47], v[128:131], v[168:171], v[44:47]
	v_mfma_f32_16x16x32_bf16 v[40:43], v[136:139], v[168:171], v[40:43]
	v_mfma_f32_16x16x32_bf16 v[28:31], v[128:131], v[192:195], v[28:31]
	v_mfma_f32_16x16x32_bf16 v[24:27], v[136:139], v[192:195], v[24:27]
	v_mfma_f32_16x16x32_bf16 v[12:15], v[128:131], v[200:203], v[12:15]
	v_mfma_f32_16x16x32_bf16 v[8:11], v[136:139], v[200:203], v[8:11]
	v_mfma_f32_16x16x32_bf16 v[60:63], v[132:135], v[164:167], v[60:63]
	v_mfma_f32_16x16x32_bf16 v[56:59], v[140:143], v[164:167], v[56:59]
	v_mfma_f32_16x16x32_bf16 v[44:47], v[132:135], v[172:175], v[44:47]
	v_mfma_f32_16x16x32_bf16 v[40:43], v[140:143], v[172:175], v[40:43]
	v_mfma_f32_16x16x32_bf16 v[28:31], v[132:135], v[196:199], v[28:31]
	v_mfma_f32_16x16x32_bf16 v[24:27], v[140:143], v[196:199], v[24:27]
	v_mfma_f32_16x16x32_bf16 v[12:15], v[132:135], v[210:213], v[12:15]
	v_mfma_f32_16x16x32_bf16 v[8:11], v[140:143], v[210:213], v[8:11]
	s_setprio 0
	s_setprio 1
	v_mfma_f32_16x16x32_bf16 v[52:55], v[144:147], v[160:163], v[52:55]
	v_mfma_f32_16x16x32_bf16 v[48:51], v[152:155], v[160:163], v[48:51]
	v_mfma_f32_16x16x32_bf16 v[36:39], v[144:147], v[168:171], v[36:39]
	v_mfma_f32_16x16x32_bf16 v[32:35], v[152:155], v[168:171], v[32:35]
	v_mfma_f32_16x16x32_bf16 v[20:23], v[144:147], v[192:195], v[20:23]
	v_mfma_f32_16x16x32_bf16 v[16:19], v[152:155], v[192:195], v[16:19]
	v_mfma_f32_16x16x32_bf16 v[4:7], v[144:147], v[200:203], v[4:7]
	v_mfma_f32_16x16x32_bf16 v[0:3], v[152:155], v[200:203], v[0:3]
	v_mfma_f32_16x16x32_bf16 v[52:55], v[148:151], v[164:167], v[52:55]
	v_mfma_f32_16x16x32_bf16 v[48:51], v[156:159], v[164:167], v[48:51]
	v_mfma_f32_16x16x32_bf16 v[36:39], v[148:151], v[172:175], v[36:39]
	v_mfma_f32_16x16x32_bf16 v[32:35], v[156:159], v[172:175], v[32:35]
	v_mfma_f32_16x16x32_bf16 v[20:23], v[148:151], v[196:199], v[20:23]
	v_mfma_f32_16x16x32_bf16 v[16:19], v[156:159], v[196:199], v[16:19]
	v_mfma_f32_16x16x32_bf16 v[4:7], v[148:151], v[210:213], v[4:7]
	v_mfma_f32_16x16x32_bf16 v[0:3], v[156:159], v[210:213], v[0:3]
	s_setprio 0
	s_barrier
	s_add_i32 s45, s45, 2
	s_add_u32 s28, s28, 0x100
	s_addc_u32 s29, s29, 0
	s_add_u32 s43, s43, 0x100
	s_addc_u32 s44, s44, 0
	s_cmp_gt_u32 s45, 13

.LBB0_768:
	s_ashr_i32 s27, s26, 31
	s_lshl_b64 s[28:29], s[26:27], 19
	s_add_u32 s28, s52, s28
	s_addc_u32 s29, s53, s29
	s_and_b64 s[30:31], s[6:7], exec
	s_cselect_b32 s27, s29, s21
	s_cselect_b32 s52, s28, s20
	s_ashr_i32 s25, s24, 31
	s_lshl_b64 s[30:31], s[24:25], 19
	s_add_u32 s30, s3, s30
	s_addc_u32 s31, s33, s31
	s_and_b64 s[34:35], s[6:7], exec
	s_cselect_b32 s25, s31, s11
	s_cselect_b32 s53, s30, s10
	s_add_u32 s34, s20, 0x40080
	s_addc_u32 s35, s21, 0
	s_add_u32 s60, s10, 0x100
	s_nop 7
	s_nop 7
	v_readlane_b32 s68, v254, 54
	s_addc_u32 s61, s11, 0
	s_mov_b32 s62, -2
	ds_read_b128 v[144:147], v151
	ds_read_b128 v[156:159], v151 offset:1024
	ds_read_b128 v[160:163], v151 offset:2048
	ds_read_b128 v[164:167], v151 offset:3072
	ds_read_b128 v[168:171], v152
	ds_read_b128 v[172:175], v152 offset:1024
	ds_read_b128 v[176:179], v152 offset:2048
	ds_read_b128 v[180:183], v152 offset:3072
	s_add_u32 s10, s34, 0xfffc0080
	s_addc_u32 s11, s35, -1
	s_cmp_eq_u32 s62, 12
	s_cselect_b32 s21, s27, s11
	s_cselect_b32 s20, s52, s10
	s_cselect_b32 s11, s25, s61
	s_cselect_b32 s10, s53, s60
	v_lshl_add_u64 v[216:217], s[34:35], 0, v[136:137]
	s_add_i32 m0, s36, 0xc000
	ds_read_b128 v[184:187], v153
	ds_read_b128 v[188:191], v153 offset:1024
	ds_read_b128 v[192:195], v153 offset:2048
	ds_read_b128 v[196:199], v153 offset:3072
	ds_read_b128 v[200:203], v153 offset:4096
	ds_read_b128 v[204:207], v153 offset:5120
	ds_read_b128 v[208:211], v153 offset:6144
	ds_read_b128 v[212:215], v153 offset:7168
	global_load_lds_dwordx4 v[216:217], off
	v_lshl_add_u64 v[216:217], s[34:35], 0, v[138:139]
	s_add_i32 m0, s36, 0xe000
	s_nop 0
	global_load_lds_dwordx4 v[216:217], off
	s_waitcnt vmcnt(8)
	s_waitcnt lgkmcnt(0)
	s_barrier
	s_setprio 1
	s_waitcnt lgkmcnt(0)
	v_mfma_f32_16x16x32_bf16 v[124:127], v[144:147], v[184:187], 0
	v_mfma_f32_16x16x32_bf16 v[120:123], v[160:163], v[184:187], 0
	v_mfma_f32_16x16x32_bf16 v[108:111], v[144:147], v[192:195], 0
	v_mfma_f32_16x16x32_bf16 v[104:107], v[160:163], v[192:195], 0
	v_mfma_f32_16x16x32_bf16 v[92:95], v[144:147], v[200:203], 0
	v_mfma_f32_16x16x32_bf16 v[88:91], v[160:163], v[200:203], 0
	v_mfma_f32_16x16x32_bf16 v[76:79], v[144:147], v[208:211], 0
	v_mfma_f32_16x16x32_bf16 v[72:75], v[160:163], v[208:211], 0
	v_mfma_f32_16x16x32_bf16 v[124:127], v[156:159], v[188:191], v[124:127]
	v_mfma_f32_16x16x32_bf16 v[120:123], v[164:167], v[188:191], v[120:123]
	v_mfma_f32_16x16x32_bf16 v[108:111], v[156:159], v[196:199], v[108:111]
	v_mfma_f32_16x16x32_bf16 v[104:107], v[164:167], v[196:199], v[104:107]
	v_mfma_f32_16x16x32_bf16 v[92:95], v[156:159], v[204:207], v[92:95]
	v_mfma_f32_16x16x32_bf16 v[88:91], v[164:167], v[204:207], v[88:91]
	v_mfma_f32_16x16x32_bf16 v[76:79], v[156:159], v[212:215], v[76:79]
	v_mfma_f32_16x16x32_bf16 v[72:75], v[164:167], v[212:215], v[72:75]
	s_setprio 0
	s_setprio 1
	v_mfma_f32_16x16x32_bf16 v[116:119], v[168:171], v[184:187], 0
	v_mfma_f32_16x16x32_bf16 v[112:115], v[176:179], v[184:187], 0
	v_mfma_f32_16x16x32_bf16 v[100:103], v[168:171], v[192:195], 0
	v_mfma_f32_16x16x32_bf16 v[96:99], v[176:179], v[192:195], 0
	v_mfma_f32_16x16x32_bf16 v[84:87], v[168:171], v[200:203], 0
	v_mfma_f32_16x16x32_bf16 v[80:83], v[176:179], v[200:203], 0
	v_mfma_f32_16x16x32_bf16 v[68:71], v[168:171], v[208:211], 0
	v_mfma_f32_16x16x32_bf16 v[64:67], v[176:179], v[208:211], 0
	v_mfma_f32_16x16x32_bf16 v[116:119], v[172:175], v[188:191], v[116:119]
	v_mfma_f32_16x16x32_bf16 v[112:115], v[180:183], v[188:191], v[112:115]
	v_mfma_f32_16x16x32_bf16 v[100:103], v[172:175], v[196:199], v[100:103]
	v_mfma_f32_16x16x32_bf16 v[96:99], v[180:183], v[196:199], v[96:99]
	v_mfma_f32_16x16x32_bf16 v[84:87], v[172:175], v[204:207], v[84:87]
	v_mfma_f32_16x16x32_bf16 v[80:83], v[180:183], v[204:207], v[80:83]
	v_mfma_f32_16x16x32_bf16 v[68:71], v[172:175], v[212:215], v[68:71]
	v_mfma_f32_16x16x32_bf16 v[64:67], v[180:183], v[212:215], v[64:67]
	s_setprio 0
	s_barrier
	s_add_i32 s63, s45, s68
	v_lshl_add_u64 v[216:217], s[10:11], 0, v[130:131]
	s_mov_b32 m0, s63
	ds_read_b128 v[184:187], v153 offset:16384
	ds_read_b128 v[188:191], v153 offset:17408
	ds_read_b128 v[192:195], v153 offset:18432
	ds_read_b128 v[196:199], v153 offset:19456
	ds_read_b128 v[200:203], v153 offset:20480
	ds_read_b128 v[204:207], v153 offset:21504
	ds_read_b128 v[208:211], v153 offset:22528
	ds_read_b128 v[212:215], v153 offset:23552
	global_load_lds_dwordx4 v[216:217], off
	s_add_i32 m0, s63, 0x2000
	s_add_u32 s64, s10, 0x40000
	v_lshl_add_u64 v[218:219], s[10:11], 0, v[134:135]
	s_addc_u32 s65, s11, 0
	s_add_i32 s63, s46, s68
	global_load_lds_dwordx4 v[218:219], off
	v_lshl_add_u64 v[220:221], s[64:65], 0, v[130:131]
	s_mov_b32 m0, s63
	v_lshl_add_u64 v[222:223], s[20:21], 0, v[132:133]
	global_load_lds_dwordx4 v[220:221], off
	v_lshl_add_u64 v[220:221], s[64:65], 0, v[134:135]
	s_add_i32 m0, s63, 0x2000
	s_nop 0
	global_load_lds_dwordx4 v[220:221], off
	v_lshl_add_u64 v[220:221], s[20:21], 0, v[128:129]
	s_mov_b32 m0, s36
	s_nop 0
	global_load_lds_dwordx4 v[220:221], off
	s_mov_b32 m0, s37
	s_nop 0
	global_load_lds_dwordx4 v[222:223], off
	s_waitcnt vmcnt(8)
	s_waitcnt lgkmcnt(0)
	s_barrier
	s_setprio 1
	s_waitcnt lgkmcnt(0)
	v_mfma_f32_16x16x32_bf16 v[60:63], v[144:147], v[184:187], 0
	v_mfma_f32_16x16x32_bf16 v[56:59], v[160:163], v[184:187], 0
	v_mfma_f32_16x16x32_bf16 v[44:47], v[144:147], v[192:195], 0
	v_mfma_f32_16x16x32_bf16 v[40:43], v[160:163], v[192:195], 0
	v_mfma_f32_16x16x32_bf16 v[28:31], v[144:147], v[200:203], 0
	v_mfma_f32_16x16x32_bf16 v[24:27], v[160:163], v[200:203], 0
	v_mfma_f32_16x16x32_bf16 v[12:15], v[144:147], v[208:211], 0
	v_mfma_f32_16x16x32_bf16 v[8:11], v[160:163], v[208:211], 0
	v_mfma_f32_16x16x32_bf16 v[60:63], v[156:159], v[188:191], v[60:63]
	v_mfma_f32_16x16x32_bf16 v[56:59], v[164:167], v[188:191], v[56:59]
	v_mfma_f32_16x16x32_bf16 v[44:47], v[156:159], v[196:199], v[44:47]
	v_mfma_f32_16x16x32_bf16 v[40:43], v[164:167], v[196:199], v[40:43]
	v_mfma_f32_16x16x32_bf16 v[28:31], v[156:159], v[204:207], v[28:31]
	v_mfma_f32_16x16x32_bf16 v[24:27], v[164:167], v[204:207], v[24:27]
	v_mfma_f32_16x16x32_bf16 v[12:15], v[156:159], v[212:215], v[12:15]
	v_mfma_f32_16x16x32_bf16 v[8:11], v[164:167], v[212:215], v[8:11]
	s_setprio 0
	s_setprio 1
	v_mfma_f32_16x16x32_bf16 v[52:55], v[168:171], v[184:187], 0
	v_mfma_f32_16x16x32_bf16 v[48:51], v[176:179], v[184:187], 0
	v_mfma_f32_16x16x32_bf16 v[36:39], v[168:171], v[192:195], 0
	v_mfma_f32_16x16x32_bf16 v[32:35], v[176:179], v[192:195], 0
	v_mfma_f32_16x16x32_bf16 v[20:23], v[168:171], v[200:203], 0
	v_mfma_f32_16x16x32_bf16 v[16:19], v[176:179], v[200:203], 0
	v_mfma_f32_16x16x32_bf16 v[4:7], v[168:171], v[208:211], 0
	v_mfma_f32_16x16x32_bf16 v[0:3], v[176:179], v[208:211], 0
	v_mfma_f32_16x16x32_bf16 v[52:55], v[172:175], v[188:191], v[52:55]
	v_mfma_f32_16x16x32_bf16 v[48:51], v[180:183], v[188:191], v[48:51]
	v_mfma_f32_16x16x32_bf16 v[36:39], v[172:175], v[196:199], v[36:39]
	v_mfma_f32_16x16x32_bf16 v[32:35], v[180:183], v[196:199], v[32:35]
	v_mfma_f32_16x16x32_bf16 v[20:23], v[172:175], v[204:207], v[20:23]
	v_mfma_f32_16x16x32_bf16 v[16:19], v[180:183], v[204:207], v[16:19]
	v_mfma_f32_16x16x32_bf16 v[4:7], v[172:175], v[212:215], v[4:7]
	v_mfma_f32_16x16x32_bf16 v[0:3], v[180:183], v[212:215], v[0:3]
	s_setprio 0
	s_barrier
	s_add_i32 s63, 0, 0x18000
	v_add_u32_e32 v155, s63, v149
	s_add_i32 s64, 0, 0x1c000
	ds_read_b128 v[144:147], v155
	ds_read_b128 v[156:159], v155 offset:1024
	ds_read_b128 v[160:163], v155 offset:2048
	ds_read_b128 v[164:167], v155 offset:3072
	v_add_u32_e32 v155, s64, v149
	ds_read_b128 v[168:171], v155
	ds_read_b128 v[172:175], v155 offset:1024
	ds_read_b128 v[176:179], v155 offset:2048
	ds_read_b128 v[180:183], v155 offset:3072
	s_add_u32 s20, s20, 0x40000
	s_addc_u32 s21, s21, 0
	s_mov_b32 m0, s38
	v_lshl_add_u64 v[224:225], s[20:21], 0, v[128:129]
	ds_read_b128 v[184:187], v153 offset:32768
	ds_read_b128 v[188:191], v153 offset:33792
	ds_read_b128 v[192:195], v153 offset:34816
	ds_read_b128 v[196:199], v153 offset:35840
	ds_read_b128 v[200:203], v153 offset:36864
	ds_read_b128 v[204:207], v153 offset:37888
	ds_read_b128 v[208:211], v153 offset:38912
	ds_read_b128 v[212:215], v153 offset:39936
	global_load_lds_dwordx4 v[224:225], off
	v_lshl_add_u64 v[224:225], s[20:21], 0, v[132:133]
	s_mov_b32 m0, s39
	s_nop 0
	global_load_lds_dwordx4 v[224:225], off
	s_waitcnt vmcnt(8)
	s_waitcnt lgkmcnt(0)
	s_barrier
	s_setprio 1
	s_waitcnt lgkmcnt(0)
	v_mfma_f32_16x16x32_bf16 v[124:127], v[144:147], v[184:187], v[124:127]
	v_mfma_f32_16x16x32_bf16 v[120:123], v[160:163], v[184:187], v[120:123]
	v_mfma_f32_16x16x32_bf16 v[108:111], v[144:147], v[192:195], v[108:111]
	v_mfma_f32_16x16x32_bf16 v[104:107], v[160:163], v[192:195], v[104:107]
	v_mfma_f32_16x16x32_bf16 v[92:95], v[144:147], v[200:203], v[92:95]
	v_mfma_f32_16x16x32_bf16 v[88:91], v[160:163], v[200:203], v[88:91]
	v_mfma_f32_16x16x32_bf16 v[76:79], v[144:147], v[208:211], v[76:79]
	v_mfma_f32_16x16x32_bf16 v[72:75], v[160:163], v[208:211], v[72:75]
	v_mfma_f32_16x16x32_bf16 v[124:127], v[156:159], v[188:191], v[124:127]
	v_mfma_f32_16x16x32_bf16 v[120:123], v[164:167], v[188:191], v[120:123]
	v_mfma_f32_16x16x32_bf16 v[108:111], v[156:159], v[196:199], v[108:111]
	v_mfma_f32_16x16x32_bf16 v[104:107], v[164:167], v[196:199], v[104:107]
	v_mfma_f32_16x16x32_bf16 v[92:95], v[156:159], v[204:207], v[92:95]
	v_mfma_f32_16x16x32_bf16 v[88:91], v[164:167], v[204:207], v[88:91]
	v_mfma_f32_16x16x32_bf16 v[76:79], v[156:159], v[212:215], v[76:79]
	v_mfma_f32_16x16x32_bf16 v[72:75], v[164:167], v[212:215], v[72:75]
	s_setprio 0
	s_setprio 1
	v_mfma_f32_16x16x32_bf16 v[116:119], v[168:171], v[184:187], v[116:119]
	v_mfma_f32_16x16x32_bf16 v[112:115], v[176:179], v[184:187], v[112:115]
	v_mfma_f32_16x16x32_bf16 v[100:103], v[168:171], v[192:195], v[100:103]
	v_mfma_f32_16x16x32_bf16 v[96:99], v[176:179], v[192:195], v[96:99]
	v_mfma_f32_16x16x32_bf16 v[84:87], v[168:171], v[200:203], v[84:87]
	v_mfma_f32_16x16x32_bf16 v[80:83], v[176:179], v[200:203], v[80:83]
	v_mfma_f32_16x16x32_bf16 v[68:71], v[168:171], v[208:211], v[68:71]
	v_mfma_f32_16x16x32_bf16 v[64:67], v[176:179], v[208:211], v[64:67]
	v_mfma_f32_16x16x32_bf16 v[116:119], v[172:175], v[188:191], v[116:119]
	v_mfma_f32_16x16x32_bf16 v[112:115], v[180:183], v[188:191], v[112:115]
	v_mfma_f32_16x16x32_bf16 v[100:103], v[172:175], v[196:199], v[100:103]
	v_mfma_f32_16x16x32_bf16 v[96:99], v[180:183], v[196:199], v[96:99]
	v_mfma_f32_16x16x32_bf16 v[84:87], v[172:175], v[204:207], v[84:87]
	v_mfma_f32_16x16x32_bf16 v[80:83], v[180:183], v[204:207], v[80:83]
	v_mfma_f32_16x16x32_bf16 v[68:71], v[172:175], v[212:215], v[68:71]
	v_mfma_f32_16x16x32_bf16 v[64:67], v[180:183], v[212:215], v[64:67]
	s_setprio 0
	s_barrier
	s_add_i32 s20, s63, s68
	v_lshl_add_u64 v[216:217], v[216:217], 0, s[14:15]
	s_mov_b32 m0, s20
	ds_read_b128 v[184:187], v153 offset:49152
	ds_read_b128 v[188:191], v153 offset:50176
	ds_read_b128 v[192:195], v153 offset:51200
	ds_read_b128 v[196:199], v153 offset:52224
	ds_read_b128 v[200:203], v153 offset:53248
	ds_read_b128 v[204:207], v153 offset:54272
	ds_read_b128 v[208:211], v153 offset:55296
	ds_read_b128 v[212:215], v153 offset:56320
	global_load_lds_dwordx4 v[216:217], off
	s_add_i32 m0, s20, 0x2000
	s_add_u32 s10, s10, 0x40080
	v_lshl_add_u64 v[216:217], v[218:219], 0, s[14:15]
	s_addc_u32 s11, s11, 0
	s_add_i32 s20, s64, s68
	global_load_lds_dwordx4 v[216:217], off
	v_lshl_add_u64 v[216:217], s[10:11], 0, v[130:131]
	s_mov_b32 m0, s20
	s_nop 0
	global_load_lds_dwordx4 v[216:217], off
	v_lshl_add_u64 v[216:217], s[10:11], 0, v[134:135]
	s_add_i32 m0, s20, 0x2000
	s_nop 0
	global_load_lds_dwordx4 v[216:217], off
	v_lshl_add_u64 v[216:217], v[220:221], 0, s[14:15]
	s_mov_b32 m0, s41
	s_nop 0
	global_load_lds_dwordx4 v[216:217], off
	v_lshl_add_u64 v[216:217], v[222:223], 0, s[14:15]
	s_mov_b32 m0, s42
	s_nop 0
	global_load_lds_dwordx4 v[216:217], off
	s_waitcnt vmcnt(8)
	s_waitcnt lgkmcnt(0)
	s_barrier
	s_setprio 1
	s_waitcnt lgkmcnt(0)
	v_mfma_f32_16x16x32_bf16 v[60:63], v[144:147], v[184:187], v[60:63]
	v_mfma_f32_16x16x32_bf16 v[56:59], v[160:163], v[184:187], v[56:59]
	v_mfma_f32_16x16x32_bf16 v[44:47], v[144:147], v[192:195], v[44:47]
	v_mfma_f32_16x16x32_bf16 v[40:43], v[160:163], v[192:195], v[40:43]
	v_mfma_f32_16x16x32_bf16 v[28:31], v[144:147], v[200:203], v[28:31]
	v_mfma_f32_16x16x32_bf16 v[24:27], v[160:163], v[200:203], v[24:27]
	v_mfma_f32_16x16x32_bf16 v[12:15], v[144:147], v[208:211], v[12:15]
	v_mfma_f32_16x16x32_bf16 v[8:11], v[160:163], v[208:211], v[8:11]
	v_mfma_f32_16x16x32_bf16 v[60:63], v[156:159], v[188:191], v[60:63]
	v_mfma_f32_16x16x32_bf16 v[56:59], v[164:167], v[188:191], v[56:59]
	v_mfma_f32_16x16x32_bf16 v[44:47], v[156:159], v[196:199], v[44:47]
	v_mfma_f32_16x16x32_bf16 v[40:43], v[164:167], v[196:199], v[40:43]
	v_mfma_f32_16x16x32_bf16 v[28:31], v[156:159], v[204:207], v[28:31]
	v_mfma_f32_16x16x32_bf16 v[24:27], v[164:167], v[204:207], v[24:27]
	v_mfma_f32_16x16x32_bf16 v[12:15], v[156:159], v[212:215], v[12:15]
	v_mfma_f32_16x16x32_bf16 v[8:11], v[164:167], v[212:215], v[8:11]
	s_setprio 0
	s_setprio 1
	v_mfma_f32_16x16x32_bf16 v[52:55], v[168:171], v[184:187], v[52:55]
	v_mfma_f32_16x16x32_bf16 v[48:51], v[176:179], v[184:187], v[48:51]
	v_mfma_f32_16x16x32_bf16 v[36:39], v[168:171], v[192:195], v[36:39]
	v_mfma_f32_16x16x32_bf16 v[32:35], v[176:179], v[192:195], v[32:35]
	v_mfma_f32_16x16x32_bf16 v[20:23], v[168:171], v[200:203], v[20:23]
	v_mfma_f32_16x16x32_bf16 v[16:19], v[176:179], v[200:203], v[16:19]
	v_mfma_f32_16x16x32_bf16 v[4:7], v[168:171], v[208:211], v[4:7]
	v_mfma_f32_16x16x32_bf16 v[0:3], v[176:179], v[208:211], v[0:3]
	v_mfma_f32_16x16x32_bf16 v[52:55], v[172:175], v[188:191], v[52:55]
	v_mfma_f32_16x16x32_bf16 v[48:51], v[180:183], v[188:191], v[48:51]
	v_mfma_f32_16x16x32_bf16 v[36:39], v[172:175], v[196:199], v[36:39]
	v_mfma_f32_16x16x32_bf16 v[32:35], v[180:183], v[196:199], v[32:35]
	v_mfma_f32_16x16x32_bf16 v[20:23], v[172:175], v[204:207], v[20:23]
	v_mfma_f32_16x16x32_bf16 v[16:19], v[180:183], v[204:207], v[16:19]
	v_mfma_f32_16x16x32_bf16 v[4:7], v[172:175], v[212:215], v[4:7]
	v_mfma_f32_16x16x32_bf16 v[0:3], v[180:183], v[212:215], v[0:3]
	s_setprio 0
	s_barrier
	s_add_i32 s62, s62, 2
	s_add_u32 s34, s34, 0x100
	s_addc_u32 s35, s35, 0
	s_add_u32 s60, s60, 0x100
	s_addc_u32 s61, s61, 0
	s_cmp_gt_u32 s62, 13

.LBB0_831:
	v_mbcnt_lo_u32_b32 v199, -1, 0
	v_mbcnt_hi_u32_b32 v199, -1, v199
	v_lshlrev_b32_e32 v199, 2, v199
	v_readlane_b32 s100, v254, 40
	v_readlane_b32 s101, v254, 41
	s_nop 4
	global_load_dword v200, v199, s[100:101]
	global_load_dword v201, v199, s[100:101] offset:256
	global_load_dword v202, v199, s[100:101] offset:512
	global_load_dword v203, v199, s[100:101] offset:768
	v_readlane_b32 s100, v254, 42
	v_readlane_b32 s101, v254, 43
	s_nop 4
	global_load_dword v204, v199, s[100:101]
	global_load_dword v205, v199, s[100:101] offset:256
	global_load_dword v206, v199, s[100:101] offset:512
	global_load_dword v207, v199, s[100:101] offset:768
	v_readlane_b32 s8, v254, 28
	s_waitcnt lgkmcnt(0)
	s_barrier
	v_mbcnt_lo_u32_b32 v144, -1, 0
	v_mbcnt_hi_u32_b32 v144, -1, v144
	v_readlane_b32 s16, v254, 36
	v_ashrrev_i32_e32 v145, 31, v144
	v_readlane_b32 s17, v254, 37
	v_readlane_b32 s18, v254, 38
	v_readlane_b32 s19, v254, 39
	v_readlane_b32 s20, v254, 40
	v_readlane_b32 s21, v254, 41
	v_lshlrev_b64 v[0:1], 2, v[144:145]
	v_readlane_b32 s22, v254, 42
	v_readlane_b32 s23, v254, 43
	s_mov_b64 s[16:17], s[20:21]
	s_mov_b64 s[18:19], s[22:23]
	v_lshl_add_u64 v[2:3], s[16:17], 0, v[0:1]
	v_lshl_add_u64 v[0:1], s[18:19], 0, v[0:1]
	s_waitcnt vmcnt(0)
	v_mov_b32_e32 v4, v200
	v_mov_b32_e32 v5, v201
	v_mov_b32_e32 v6, v202
	v_mov_b32_e32 v7, v203
	v_mov_b32_e32 v8, v204
	v_mov_b32_e32 v9, v205
	v_mov_b32_e32 v10, v206
	v_mov_b32_e32 v11, v207
	s_add_u32 s2, s74, 0x6600000
	s_mov_b32 s1, 0
	s_addc_u32 s3, s75, 0
	s_and_b64 vcc, exec, s[4:5]
	v_readlane_b32 s9, v254, 29
	v_readlane_b32 s10, v254, 30
	v_readlane_b32 s11, v254, 31
	v_readlane_b32 s12, v254, 32
	v_readlane_b32 s13, v254, 33
	v_readlane_b32 s14, v254, 34
	v_readlane_b32 s15, v254, 35
	s_waitcnt vmcnt(0)
	v_max3_f32 v0, |v4|, 0, |v5|
	v_mov_b32_e32 v4, 0xc2700000
	v_max3_f32 v0, v0, |v6|, |v7|
	ds_swizzle_b32 v2, v0 offset:swizzle(SWAP,1)
	v_max3_f32 v1, |v8|, 0, |v9|
	v_max3_f32 v1, v1, |v10|, |v11|
	ds_swizzle_b32 v3, v1 offset:swizzle(SWAP,1)
	s_waitcnt lgkmcnt(1)
	v_max_f32_e32 v2, v2, v2
	v_max_f32_e32 v0, v0, v2
	ds_swizzle_b32 v2, v0 offset:swizzle(SWAP,2)
	s_waitcnt lgkmcnt(1)
	v_max_f32_e32 v3, v3, v3
	v_max_f32_e32 v1, v1, v3
	ds_swizzle_b32 v3, v1 offset:swizzle(SWAP,2)
	s_waitcnt lgkmcnt(1)
	v_max_f32_e32 v2, v2, v2
	v_max_f32_e32 v0, v0, v2
	ds_swizzle_b32 v2, v0 offset:swizzle(SWAP,4)
	s_waitcnt lgkmcnt(1)
	v_max_f32_e32 v3, v3, v3
	v_max_f32_e32 v1, v1, v3
	ds_swizzle_b32 v3, v1 offset:swizzle(SWAP,4)
	s_waitcnt lgkmcnt(1)
	v_max_f32_e32 v2, v2, v2
	v_max_f32_e32 v0, v0, v2
	ds_swizzle_b32 v2, v0 offset:swizzle(SWAP,8)
	s_waitcnt lgkmcnt(1)
	v_max_f32_e32 v3, v3, v3
	v_max_f32_e32 v1, v1, v3
	ds_swizzle_b32 v3, v1 offset:swizzle(SWAP,8)
	s_waitcnt lgkmcnt(1)
	v_max_f32_e32 v2, v2, v2
	v_max_f32_e32 v0, v0, v2
	ds_swizzle_b32 v2, v0 offset:swizzle(SWAP,16)
	s_waitcnt lgkmcnt(1)
	v_max_f32_e32 v3, v3, v3
	v_max_f32_e32 v1, v1, v3
	ds_swizzle_b32 v3, v1 offset:swizzle(SWAP,16)
	s_waitcnt lgkmcnt(1)
	v_max_f32_e32 v2, v2, v2
	v_max_f32_e32 v0, v0, v2
	v_mov_b32_e32 v2, v0
	s_nop 1
	v_permlane32_swap_b32_e32 v0, v2
	s_waitcnt lgkmcnt(0)
	v_max_f32_e32 v3, v3, v3
	v_max_f32_e32 v1, v1, v3
	v_mov_b32_e32 v3, v1
	s_nop 1
	v_permlane32_swap_b32_e32 v1, v3
	v_max_f32_e32 v2, v2, v2
	v_max_f32_e32 v0, v0, v0
	v_max_f32_e32 v3, v3, v3
	v_max_f32_e32 v1, v1, v1
	v_max_f32_e32 v0, v0, v2
	v_max_f32_e32 v1, v1, v3
	v_mul_f32_e32 v0, v0, v1
	v_mul_f32_e32 v0, 0x43800000, v0
	v_fmac_f32_e32 v4, 0x3db8aa3b, v0
	v_max_f32_e32 v0, 0, v4
	s_nop 0
	v_readfirstlane_b32 s7, v0
	s_cbranch_vccnz .LBB0_844
	v_readlane_b32 s0, v254, 44
	v_and_b32_e32 v4, 7, v144
	v_readlane_b32 s4, v254, 45
	v_add_u32_e32 v2, s0, v144
	v_lshlrev_b32_e32 v3, 2, v144
	s_add_i32 s0, 0, 0x20000
	v_mov_b32_e32 v149, 0
	v_lshlrev_b32_e32 v148, 4, v4
	v_readlane_b32 s5, v254, 46
	v_readlane_b32 s8, v254, 52
	v_and_b32_e32 v1, 31, v144
	v_add_u32_e32 v161, s0, v3
	v_lshl_add_u64 v[150:151], s[4:5], 0, v[148:149]
	s_add_i32 s0, 0, 0x10000
	s_lshl_b32 s4, s8, 14
	s_add_i32 s4, s0, s4
	v_lshlrev_b32_e32 v7, 9, v1
	v_add_u32_e32 v166, s4, v7
	v_lshlrev_b32_e32 v9, 4, v144
	s_movk_i32 s4, 0x70
	v_ashrrev_i32_e32 v146, 3, v2
	v_bitop3_b32 v2, v2, s4, v9 bitop3:0x48
	v_and_b32_e32 v9, 19, v144
	v_lshlrev_b32_e32 v10, 1, v144
	v_lshrrev_b32_e32 v11, 1, v144
	v_readlane_b32 s5, v254, 48
	v_and_b32_e32 v10, 8, v10
	v_and_or_b32 v9, v11, 4, v9
	s_lshl_b32 s4, s5, 14
	v_or_b32_e32 v12, v9, v10
	s_add_i32 s4, s4, 0
	v_readlane_b32 s6, v254, 25
	v_ashrrev_i32_e32 v145, 5, v144
	v_lshl_add_u32 v168, v12, 9, s4
	s_and_b32 s4, s6, 0x3fffffc
	v_bitop3_b32 v169, v9, 15, v10 bitop3:0xc8
	v_add_u32_e32 v9, s4, v145
	s_lshl_b32 s4, s8, 15
	s_add_i32 s11, s4, 0
	v_lshlrev_b32_e32 v5, 9, v146
	v_add_u32_e32 v171, s11, v3
	v_lshlrev_b32_e32 v3, 3, v145
	v_and_b32_e32 v6, 0x3e00, v5
	v_add3_u32 v172, s11, v7, v3
	v_and_b32_e32 v3, 0xffffc000, v5
	v_add3_u32 v173, s0, v6, v3
	v_bitop3_b32 v3, v146, v4, 15 bitop3:0x6c
	v_lshlrev_b32_e32 v148, 5, v4
	v_lshlrev_b32_e32 v174, 4, v3
	v_or_b32_e32 v3, 8, v4
	v_lshl_add_u64 v[152:153], s[16:17], 0, v[148:149]
	v_lshlrev_b32_e32 v148, 5, v3
	v_bitop3_b32 v3, v146, v3, 15 bitop3:0x6c
	v_lshlrev_b32_e32 v175, 4, v3
	v_or_b32_e32 v3, 16, v4
	v_lshl_add_u64 v[154:155], s[16:17], 0, v[148:149]
	v_lshlrev_b32_e32 v148, 5, v3
	v_bitop3_b32 v3, v146, v3, 15 bitop3:0x6c
	v_lshlrev_b32_e32 v176, 4, v3
	v_or_b32_e32 v3, 24, v4
	v_lshlrev_b32_e32 v0, 3, v4
	v_lshl_add_u64 v[156:157], s[16:17], 0, v[148:149]
	v_lshlrev_b32_e32 v148, 5, v3
	v_bitop3_b32 v3, v146, v3, 15 bitop3:0x6c
	v_add_u32_e32 v4, 2, v9
	v_lshlrev_b32_e32 v177, 4, v3
	v_bitop3_b32 v3, v9, v11, 7 bitop3:0x78
	v_bitop3_b32 v4, v4, v11, 7 bitop3:0x78
	v_lshlrev_b32_e32 v178, 4, v1
	v_add_u32_e32 v167, 0, v5
	v_lshl_add_u32 v8, v146, 7, 0
	v_lshl_add_u32 v10, v1, 7, 0
	s_cmp_eq_u32 s5, 1
	v_lshlrev_b32_e32 v3, 4, v3
	v_lshlrev_b32_e32 v4, 4, v4
	v_xor_b32_e32 v1, 16, v178
	v_xor_b32_e32 v5, 32, v178
	v_xor_b32_e32 v6, 48, v178
	v_xor_b32_e32 v7, 64, v178
	v_xor_b32_e32 v9, 0x50, v178
	v_xor_b32_e32 v11, 0x60, v178
	v_xor_b32_e32 v12, 0x70, v178
	v_xor_b32_e32 v13, 0x80, v178
	v_xor_b32_e32 v14, 0x90, v178
	v_xor_b32_e32 v15, 0xa0, v178
	v_xor_b32_e32 v16, 0xb0, v178
	v_xor_b32_e32 v17, 0xc0, v178
	v_xor_b32_e32 v18, 0xd0, v178
	v_xor_b32_e32 v19, 0xe0, v178
	v_xor_b32_e32 v20, 0xf0, v178
	v_xor_b32_e32 v21, 0x100, v178
	v_xor_b32_e32 v22, 0x110, v178
	v_xor_b32_e32 v23, 0x120, v178
	v_xor_b32_e32 v24, 0x130, v178
	v_xor_b32_e32 v25, 0x140, v178
	v_xor_b32_e32 v26, 0x150, v178
	v_xor_b32_e32 v27, 0x160, v178
	v_xor_b32_e32 v28, 0x170, v178
	v_xor_b32_e32 v29, 0x180, v178
	v_xor_b32_e32 v30, 0x190, v178
	v_xor_b32_e32 v31, 0x1a0, v178
	v_xor_b32_e32 v32, 0x1b0, v178
	v_xor_b32_e32 v33, 0x1c0, v178
	v_xor_b32_e32 v34, 0x1d0, v178
	v_xor_b32_e32 v35, 0x1e0, v178
	v_xor_b32_e32 v36, 0x1f0, v178
	s_mov_b32 s10, 0x20000
	v_ashrrev_i32_e32 v147, 31, v146
	v_and_b32_e32 v170, 15, v144
	s_cselect_b64 s[4:5], -1, 0
	s_lshl_b32 s12, s8, 8
	s_lshl_b32 s13, s6, 8
	v_lshl_add_u64 v[158:159], s[16:17], 0, v[148:149]
	s_mov_b32 s6, 0x3b800000
	s_mov_b32 s14, 0x800000
	v_lshlrev_b32_e32 v148, 1, v0
	v_add_u32_e32 v179, v8, v2
	v_add_u32_e32 v180, v10, v3
	v_add_u32_e32 v181, v10, v4
	v_add_u32_e32 v182, v172, v1
	v_add_u32_e32 v183, v172, v5
	v_add_u32_e32 v184, v172, v6
	v_add_u32_e32 v185, v172, v7
	v_add_u32_e32 v186, v172, v9
	v_add_u32_e32 v187, v172, v11
	v_add_u32_e32 v188, v172, v12
	v_add_u32_e32 v189, v172, v13
	v_add_u32_e32 v190, v172, v14
	v_add_u32_e32 v191, v172, v15
	v_add_u32_e32 v192, v172, v16
	v_add_u32_e32 v193, v172, v17
	v_add_u32_e32 v194, v172, v18
	v_add_u32_e32 v195, v172, v19
	v_add_u32_e32 v196, v172, v20
	v_add_u32_e32 v197, v172, v21
	v_add_u32_e32 v198, v172, v22
	v_add_u32_e32 v199, v172, v23
	v_add_u32_e32 v200, v172, v24
	v_add_u32_e32 v201, v172, v25
	v_add_u32_e32 v202, v172, v26
	v_add_u32_e32 v203, v172, v27
	v_add_u32_e32 v204, v172, v28
	v_add_u32_e32 v205, v172, v29
	v_add_u32_e32 v206, v172, v30
	v_add_u32_e32 v207, v172, v31
	v_add_u32_e32 v208, v172, v32
	v_add_u32_e32 v209, v172, v33
	v_add_u32_e32 v210, v172, v34
	v_add_u32_e32 v211, v172, v35
	v_add_u32_e32 v212, v172, v36
	v_mov_b32_e32 v160, 0x358637bd
	s_mov_b32 s15, s70
	s_cmp_eq_u32 s78, 0x100
	s_cbranch_scc0 .LBB0_834
	s_and_b32 s15, s70, 7
	s_lshr_b32 s16, s15, 2
	s_lshl_b32 s16, s16, 8
	s_and_b32 s15, s15, 3
	s_lshl_b32 s15, s15, 4
	s_or_b32 s15, s15, s16
	s_lshr_b32 s16, s70, 3
	s_and_b32 s16, s16, 7
	s_lshl_b32 s16, s16, 1
	s_or_b32 s15, s15, s16
	s_lshr_b32 s16, s70, 6
	s_lshl_b32 s16, s16, 6
	s_or_b32 s15, s15, s16
	s_branch .LBB0_834

.LBB0_916:
	s_ashr_i32 s17, s16, 31
	s_lshl_b64 s[18:19], s[16:17], 19
	s_add_u32 s18, s2, s18
	s_addc_u32 s19, s3, s19
	s_and_b64 s[22:23], s[6:7], exec
	s_cselect_b32 s17, s19, s21
	s_cselect_b32 s43, s18, s20
	s_ashr_i32 s15, s14, 31
	s_lshl_b64 s[22:23], s[14:15], 19
	s_add_u32 s22, s30, s22
	s_addc_u32 s23, s31, s23
	s_and_b64 s[28:29], s[6:7], exec
	s_cselect_b32 s15, s23, s11
	s_cselect_b32 s44, s22, s10
	s_add_u32 s28, s20, 0x40080
	s_addc_u32 s29, s21, 0
	s_add_u32 s45, s10, 0x100
	s_nop 7
	s_nop 7
	v_readlane_b32 s51, v254, 54
	s_addc_u32 s46, s11, 0
	s_mov_b32 s47, -2
	ds_read_b128 v[128:131], v213
	ds_read_b128 v[132:135], v213 offset:1024
	ds_read_b128 v[136:139], v213 offset:2048
	ds_read_b128 v[140:143], v213 offset:3072
	ds_read_b128 v[144:147], v214
	ds_read_b128 v[148:151], v214 offset:1024
	ds_read_b128 v[152:155], v214 offset:2048
	ds_read_b128 v[156:159], v214 offset:3072
	s_add_u32 s10, s28, 0xfffc0080
	s_addc_u32 s11, s29, -1
	s_cmp_eq_u32 s47, 12
	s_cselect_b32 s21, s17, s11
	s_cselect_b32 s20, s43, s10
	s_cselect_b32 s11, s15, s46
	s_cselect_b32 s10, s44, s45
	v_lshl_add_u64 v[208:209], s[28:29], 0, v[184:185]
	s_add_i32 m0, s25, 0xc000
	ds_read_b128 v[160:163], v215
	ds_read_b128 v[164:167], v215 offset:1024
	ds_read_b128 v[168:171], v215 offset:2048
	ds_read_b128 v[172:175], v215 offset:3072
	ds_read_b128 v[192:195], v215 offset:4096
	ds_read_b128 v[196:199], v215 offset:5120
	ds_read_b128 v[200:203], v215 offset:6144
	ds_read_b128 v[204:207], v215 offset:7168
	global_load_lds_dwordx4 v[208:209], off
	v_lshl_add_u64 v[208:209], s[28:29], 0, v[186:187]
	s_add_i32 m0, s25, 0xe000
	s_nop 0
	global_load_lds_dwordx4 v[208:209], off
	s_waitcnt vmcnt(8)
	s_waitcnt lgkmcnt(0)
	s_barrier
	s_setprio 1
	s_waitcnt lgkmcnt(0)
	v_mfma_f32_16x16x32_bf16 v[124:127], v[128:131], v[160:163], 0
	v_mfma_f32_16x16x32_bf16 v[120:123], v[136:139], v[160:163], 0
	v_mfma_f32_16x16x32_bf16 v[108:111], v[128:131], v[168:171], 0
	v_mfma_f32_16x16x32_bf16 v[104:107], v[136:139], v[168:171], 0
	v_mfma_f32_16x16x32_bf16 v[92:95], v[128:131], v[192:195], 0
	v_mfma_f32_16x16x32_bf16 v[88:91], v[136:139], v[192:195], 0
	v_mfma_f32_16x16x32_bf16 v[76:79], v[128:131], v[200:203], 0
	v_mfma_f32_16x16x32_bf16 v[72:75], v[136:139], v[200:203], 0
	v_mfma_f32_16x16x32_bf16 v[124:127], v[132:135], v[164:167], v[124:127]
	v_mfma_f32_16x16x32_bf16 v[120:123], v[140:143], v[164:167], v[120:123]
	v_mfma_f32_16x16x32_bf16 v[108:111], v[132:135], v[172:175], v[108:111]
	v_mfma_f32_16x16x32_bf16 v[104:107], v[140:143], v[172:175], v[104:107]
	v_mfma_f32_16x16x32_bf16 v[92:95], v[132:135], v[196:199], v[92:95]
	v_mfma_f32_16x16x32_bf16 v[88:91], v[140:143], v[196:199], v[88:91]
	v_mfma_f32_16x16x32_bf16 v[76:79], v[132:135], v[204:207], v[76:79]
	v_mfma_f32_16x16x32_bf16 v[72:75], v[140:143], v[204:207], v[72:75]
	s_setprio 0
	s_setprio 1
	v_mfma_f32_16x16x32_bf16 v[116:119], v[144:147], v[160:163], 0
	v_mfma_f32_16x16x32_bf16 v[112:115], v[152:155], v[160:163], 0
	v_mfma_f32_16x16x32_bf16 v[100:103], v[144:147], v[168:171], 0
	v_mfma_f32_16x16x32_bf16 v[96:99], v[152:155], v[168:171], 0
	v_mfma_f32_16x16x32_bf16 v[84:87], v[144:147], v[192:195], 0
	v_mfma_f32_16x16x32_bf16 v[80:83], v[152:155], v[192:195], 0
	v_mfma_f32_16x16x32_bf16 v[68:71], v[144:147], v[200:203], 0
	v_mfma_f32_16x16x32_bf16 v[64:67], v[152:155], v[200:203], 0
	v_mfma_f32_16x16x32_bf16 v[116:119], v[148:151], v[164:167], v[116:119]
	v_mfma_f32_16x16x32_bf16 v[112:115], v[156:159], v[164:167], v[112:115]
	v_mfma_f32_16x16x32_bf16 v[100:103], v[148:151], v[172:175], v[100:103]
	v_mfma_f32_16x16x32_bf16 v[96:99], v[156:159], v[172:175], v[96:99]
	v_mfma_f32_16x16x32_bf16 v[84:87], v[148:151], v[196:199], v[84:87]
	v_mfma_f32_16x16x32_bf16 v[80:83], v[156:159], v[196:199], v[80:83]
	v_mfma_f32_16x16x32_bf16 v[68:71], v[148:151], v[204:207], v[68:71]
	v_mfma_f32_16x16x32_bf16 v[64:67], v[156:159], v[204:207], v[64:67]
	s_setprio 0
	s_barrier
	s_add_i32 s48, s41, s51
	v_lshl_add_u64 v[208:209], s[10:11], 0, v[178:179]
	s_mov_b32 m0, s48
	ds_read_b128 v[160:163], v215 offset:16384
	ds_read_b128 v[164:167], v215 offset:17408
	ds_read_b128 v[168:171], v215 offset:18432
	ds_read_b128 v[172:175], v215 offset:19456
	ds_read_b128 v[192:195], v215 offset:20480
	ds_read_b128 v[196:199], v215 offset:21504
	ds_read_b128 v[200:203], v215 offset:22528
	ds_read_b128 v[204:207], v215 offset:23552
	global_load_lds_dwordx4 v[208:209], off
	s_add_i32 m0, s48, 0x2000
	s_add_u32 s48, s10, 0x40000
	v_lshl_add_u64 v[216:217], s[10:11], 0, v[182:183]
	s_addc_u32 s49, s11, 0
	s_add_i32 s50, s42, s51
	global_load_lds_dwordx4 v[216:217], off
	v_lshl_add_u64 v[218:219], s[48:49], 0, v[178:179]
	s_mov_b32 m0, s50
	v_lshl_add_u64 v[220:221], s[20:21], 0, v[180:181]
	global_load_lds_dwordx4 v[218:219], off
	v_lshl_add_u64 v[218:219], s[48:49], 0, v[182:183]
	s_add_i32 m0, s50, 0x2000
	s_nop 0
	global_load_lds_dwordx4 v[218:219], off
	v_lshl_add_u64 v[218:219], s[20:21], 0, v[176:177]
	s_mov_b32 m0, s25
	s_nop 0
	global_load_lds_dwordx4 v[218:219], off
	s_mov_b32 m0, s27
	s_nop 0
	global_load_lds_dwordx4 v[220:221], off
	s_waitcnt vmcnt(8)
	s_waitcnt lgkmcnt(0)
	s_barrier
	s_setprio 1
	s_waitcnt lgkmcnt(0)
	v_mfma_f32_16x16x32_bf16 v[60:63], v[128:131], v[160:163], 0
	v_mfma_f32_16x16x32_bf16 v[56:59], v[136:139], v[160:163], 0
	v_mfma_f32_16x16x32_bf16 v[44:47], v[128:131], v[168:171], 0
	v_mfma_f32_16x16x32_bf16 v[40:43], v[136:139], v[168:171], 0
	v_mfma_f32_16x16x32_bf16 v[28:31], v[128:131], v[192:195], 0
	v_mfma_f32_16x16x32_bf16 v[24:27], v[136:139], v[192:195], 0
	v_mfma_f32_16x16x32_bf16 v[12:15], v[128:131], v[200:203], 0
	v_mfma_f32_16x16x32_bf16 v[8:11], v[136:139], v[200:203], 0
	v_mfma_f32_16x16x32_bf16 v[60:63], v[132:135], v[164:167], v[60:63]
	v_mfma_f32_16x16x32_bf16 v[56:59], v[140:143], v[164:167], v[56:59]
	v_mfma_f32_16x16x32_bf16 v[44:47], v[132:135], v[172:175], v[44:47]
	v_mfma_f32_16x16x32_bf16 v[40:43], v[140:143], v[172:175], v[40:43]
	v_mfma_f32_16x16x32_bf16 v[28:31], v[132:135], v[196:199], v[28:31]
	v_mfma_f32_16x16x32_bf16 v[24:27], v[140:143], v[196:199], v[24:27]
	v_mfma_f32_16x16x32_bf16 v[12:15], v[132:135], v[204:207], v[12:15]
	v_mfma_f32_16x16x32_bf16 v[8:11], v[140:143], v[204:207], v[8:11]
	s_setprio 0
	s_setprio 1
	v_mfma_f32_16x16x32_bf16 v[52:55], v[144:147], v[160:163], 0
	v_mfma_f32_16x16x32_bf16 v[48:51], v[152:155], v[160:163], 0
	v_mfma_f32_16x16x32_bf16 v[36:39], v[144:147], v[168:171], 0
	v_mfma_f32_16x16x32_bf16 v[32:35], v[152:155], v[168:171], 0
	v_mfma_f32_16x16x32_bf16 v[20:23], v[144:147], v[192:195], 0
	v_mfma_f32_16x16x32_bf16 v[16:19], v[152:155], v[192:195], 0
	v_mfma_f32_16x16x32_bf16 v[4:7], v[144:147], v[200:203], 0
	v_mfma_f32_16x16x32_bf16 v[0:3], v[152:155], v[200:203], 0
	v_mfma_f32_16x16x32_bf16 v[52:55], v[148:151], v[164:167], v[52:55]
	v_mfma_f32_16x16x32_bf16 v[48:51], v[156:159], v[164:167], v[48:51]
	v_mfma_f32_16x16x32_bf16 v[36:39], v[148:151], v[172:175], v[36:39]
	v_mfma_f32_16x16x32_bf16 v[32:35], v[156:159], v[172:175], v[32:35]
	v_mfma_f32_16x16x32_bf16 v[20:23], v[148:151], v[196:199], v[20:23]
	v_mfma_f32_16x16x32_bf16 v[16:19], v[156:159], v[196:199], v[16:19]
	v_mfma_f32_16x16x32_bf16 v[4:7], v[148:151], v[204:207], v[4:7]
	v_mfma_f32_16x16x32_bf16 v[0:3], v[156:159], v[204:207], v[0:3]
	s_setprio 0
	s_barrier
	s_add_i32 s48, 0, 0x18000
	s_add_i32 s49, 0, 0x1c000
	v_add_u32_e32 v140, s48, v211
	v_add_u32_e32 v156, s49, v211
	ds_read_b128 v[128:131], v140
	ds_read_b128 v[132:135], v140 offset:1024
	ds_read_b128 v[136:139], v140 offset:2048
	ds_read_b128 v[140:143], v140 offset:3072
	ds_read_b128 v[144:147], v156
	ds_read_b128 v[148:151], v156 offset:1024
	ds_read_b128 v[152:155], v156 offset:2048
	ds_read_b128 v[156:159], v156 offset:3072
	s_add_u32 s20, s20, 0x40000
	s_addc_u32 s21, s21, 0
	s_mov_b32 m0, s33
	v_lshl_add_u64 v[222:223], s[20:21], 0, v[176:177]
	ds_read_b128 v[160:163], v215 offset:32768
	ds_read_b128 v[164:167], v215 offset:33792
	ds_read_b128 v[168:171], v215 offset:34816
	ds_read_b128 v[172:175], v215 offset:35840
	ds_read_b128 v[192:195], v215 offset:36864
	ds_read_b128 v[196:199], v215 offset:37888
	ds_read_b128 v[200:203], v215 offset:38912
	ds_read_b128 v[204:207], v215 offset:39936
	global_load_lds_dwordx4 v[222:223], off
	v_lshl_add_u64 v[222:223], s[20:21], 0, v[180:181]
	s_mov_b32 m0, s34
	s_nop 0
	global_load_lds_dwordx4 v[222:223], off
	s_waitcnt vmcnt(8)
	s_waitcnt lgkmcnt(0)
	s_barrier
	s_setprio 1
	s_waitcnt lgkmcnt(0)
	v_mfma_f32_16x16x32_bf16 v[124:127], v[128:131], v[160:163], v[124:127]
	v_mfma_f32_16x16x32_bf16 v[120:123], v[136:139], v[160:163], v[120:123]
	v_mfma_f32_16x16x32_bf16 v[108:111], v[128:131], v[168:171], v[108:111]
	v_mfma_f32_16x16x32_bf16 v[104:107], v[136:139], v[168:171], v[104:107]
	v_mfma_f32_16x16x32_bf16 v[92:95], v[128:131], v[192:195], v[92:95]
	v_mfma_f32_16x16x32_bf16 v[88:91], v[136:139], v[192:195], v[88:91]
	v_mfma_f32_16x16x32_bf16 v[76:79], v[128:131], v[200:203], v[76:79]
	v_mfma_f32_16x16x32_bf16 v[72:75], v[136:139], v[200:203], v[72:75]
	v_mfma_f32_16x16x32_bf16 v[124:127], v[132:135], v[164:167], v[124:127]
	v_mfma_f32_16x16x32_bf16 v[120:123], v[140:143], v[164:167], v[120:123]
	v_mfma_f32_16x16x32_bf16 v[108:111], v[132:135], v[172:175], v[108:111]
	v_mfma_f32_16x16x32_bf16 v[104:107], v[140:143], v[172:175], v[104:107]
	v_mfma_f32_16x16x32_bf16 v[92:95], v[132:135], v[196:199], v[92:95]
	v_mfma_f32_16x16x32_bf16 v[88:91], v[140:143], v[196:199], v[88:91]
	v_mfma_f32_16x16x32_bf16 v[76:79], v[132:135], v[204:207], v[76:79]
	v_mfma_f32_16x16x32_bf16 v[72:75], v[140:143], v[204:207], v[72:75]
	s_setprio 0
	s_setprio 1
	v_mfma_f32_16x16x32_bf16 v[116:119], v[144:147], v[160:163], v[116:119]
	v_mfma_f32_16x16x32_bf16 v[112:115], v[152:155], v[160:163], v[112:115]
	v_mfma_f32_16x16x32_bf16 v[100:103], v[144:147], v[168:171], v[100:103]
	v_mfma_f32_16x16x32_bf16 v[96:99], v[152:155], v[168:171], v[96:99]
	v_mfma_f32_16x16x32_bf16 v[84:87], v[144:147], v[192:195], v[84:87]
	v_mfma_f32_16x16x32_bf16 v[80:83], v[152:155], v[192:195], v[80:83]
	v_mfma_f32_16x16x32_bf16 v[68:71], v[144:147], v[200:203], v[68:71]
	v_mfma_f32_16x16x32_bf16 v[64:67], v[152:155], v[200:203], v[64:67]
	v_mfma_f32_16x16x32_bf16 v[116:119], v[148:151], v[164:167], v[116:119]
	v_mfma_f32_16x16x32_bf16 v[112:115], v[156:159], v[164:167], v[112:115]
	v_mfma_f32_16x16x32_bf16 v[100:103], v[148:151], v[172:175], v[100:103]
	v_mfma_f32_16x16x32_bf16 v[96:99], v[156:159], v[172:175], v[96:99]
	v_mfma_f32_16x16x32_bf16 v[84:87], v[148:151], v[196:199], v[84:87]
	v_mfma_f32_16x16x32_bf16 v[80:83], v[156:159], v[196:199], v[80:83]
	v_mfma_f32_16x16x32_bf16 v[68:71], v[148:151], v[204:207], v[68:71]
	v_mfma_f32_16x16x32_bf16 v[64:67], v[156:159], v[204:207], v[64:67]
	s_setprio 0
	s_barrier
	s_add_i32 s20, s48, s51
	v_lshl_add_u64 v[208:209], v[208:209], 0, s[12:13]
	s_mov_b32 m0, s20
	ds_read_b128 v[160:163], v215 offset:49152
	ds_read_b128 v[164:167], v215 offset:50176
	ds_read_b128 v[168:171], v215 offset:51200
	ds_read_b128 v[172:175], v215 offset:52224
	ds_read_b128 v[192:195], v215 offset:53248
	ds_read_b128 v[196:199], v215 offset:54272
	ds_read_b128 v[200:203], v215 offset:55296
	ds_read_b128 v[204:207], v215 offset:56320
	global_load_lds_dwordx4 v[208:209], off
	s_add_i32 m0, s20, 0x2000
	s_add_u32 s10, s10, 0x40080
	v_lshl_add_u64 v[208:209], v[216:217], 0, s[12:13]
	s_addc_u32 s11, s11, 0
	s_add_i32 s20, s49, s51
	global_load_lds_dwordx4 v[208:209], off
	v_lshl_add_u64 v[208:209], s[10:11], 0, v[178:179]
	s_mov_b32 m0, s20
	s_nop 0
	global_load_lds_dwordx4 v[208:209], off
	v_lshl_add_u64 v[208:209], s[10:11], 0, v[182:183]
	s_add_i32 m0, s20, 0x2000
	s_nop 0
	global_load_lds_dwordx4 v[208:209], off
	v_lshl_add_u64 v[208:209], v[218:219], 0, s[12:13]
	s_mov_b32 m0, s36
	s_nop 0
	global_load_lds_dwordx4 v[208:209], off
	v_lshl_add_u64 v[208:209], v[220:221], 0, s[12:13]
	s_mov_b32 m0, s37
	s_nop 0
	global_load_lds_dwordx4 v[208:209], off
	s_waitcnt vmcnt(8)
	s_waitcnt lgkmcnt(0)
	s_barrier
	s_setprio 1
	s_waitcnt lgkmcnt(0)
	v_mfma_f32_16x16x32_bf16 v[60:63], v[128:131], v[160:163], v[60:63]
	v_mfma_f32_16x16x32_bf16 v[56:59], v[136:139], v[160:163], v[56:59]
	v_mfma_f32_16x16x32_bf16 v[44:47], v[128:131], v[168:171], v[44:47]
	v_mfma_f32_16x16x32_bf16 v[40:43], v[136:139], v[168:171], v[40:43]
	v_mfma_f32_16x16x32_bf16 v[28:31], v[128:131], v[192:195], v[28:31]
	v_mfma_f32_16x16x32_bf16 v[24:27], v[136:139], v[192:195], v[24:27]
	v_mfma_f32_16x16x32_bf16 v[12:15], v[128:131], v[200:203], v[12:15]
	v_mfma_f32_16x16x32_bf16 v[8:11], v[136:139], v[200:203], v[8:11]
	v_mfma_f32_16x16x32_bf16 v[60:63], v[132:135], v[164:167], v[60:63]
	v_mfma_f32_16x16x32_bf16 v[56:59], v[140:143], v[164:167], v[56:59]
	v_mfma_f32_16x16x32_bf16 v[44:47], v[132:135], v[172:175], v[44:47]
	v_mfma_f32_16x16x32_bf16 v[40:43], v[140:143], v[172:175], v[40:43]
	v_mfma_f32_16x16x32_bf16 v[28:31], v[132:135], v[196:199], v[28:31]
	v_mfma_f32_16x16x32_bf16 v[24:27], v[140:143], v[196:199], v[24:27]
	v_mfma_f32_16x16x32_bf16 v[12:15], v[132:135], v[204:207], v[12:15]
	v_mfma_f32_16x16x32_bf16 v[8:11], v[140:143], v[204:207], v[8:11]
	s_setprio 0
	s_setprio 1
	v_mfma_f32_16x16x32_bf16 v[52:55], v[144:147], v[160:163], v[52:55]
	v_mfma_f32_16x16x32_bf16 v[48:51], v[152:155], v[160:163], v[48:51]
	v_mfma_f32_16x16x32_bf16 v[36:39], v[144:147], v[168:171], v[36:39]
	v_mfma_f32_16x16x32_bf16 v[32:35], v[152:155], v[168:171], v[32:35]
	v_mfma_f32_16x16x32_bf16 v[20:23], v[144:147], v[192:195], v[20:23]
	v_mfma_f32_16x16x32_bf16 v[16:19], v[152:155], v[192:195], v[16:19]
	v_mfma_f32_16x16x32_bf16 v[4:7], v[144:147], v[200:203], v[4:7]
	v_mfma_f32_16x16x32_bf16 v[0:3], v[152:155], v[200:203], v[0:3]
	v_mfma_f32_16x16x32_bf16 v[52:55], v[148:151], v[164:167], v[52:55]
	v_mfma_f32_16x16x32_bf16 v[48:51], v[156:159], v[164:167], v[48:51]
	v_mfma_f32_16x16x32_bf16 v[36:39], v[148:151], v[172:175], v[36:39]
	v_mfma_f32_16x16x32_bf16 v[32:35], v[156:159], v[172:175], v[32:35]
	v_mfma_f32_16x16x32_bf16 v[20:23], v[148:151], v[196:199], v[20:23]
	v_mfma_f32_16x16x32_bf16 v[16:19], v[156:159], v[196:199], v[16:19]
	v_mfma_f32_16x16x32_bf16 v[4:7], v[148:151], v[204:207], v[4:7]
	v_mfma_f32_16x16x32_bf16 v[0:3], v[156:159], v[204:207], v[0:3]
	s_setprio 0
	s_barrier
	s_add_i32 s47, s47, 2
	s_add_u32 s28, s28, 0x100
	s_addc_u32 s29, s29, 0
	s_add_u32 s45, s45, 0x100
	s_addc_u32 s46, s46, 0
	s_cmp_gt_u32 s47, 13

.LBB0_1002:
	s_ashr_i32 s17, s16, 31
	s_lshl_b64 s[18:19], s[16:17], 19
	s_add_u32 s18, s52, s18
	s_addc_u32 s19, s53, s19
	s_and_b64 s[22:23], s[4:5], exec
	s_cselect_b32 s17, s19, s21
	s_cselect_b32 s42, s18, s20
	s_ashr_i32 s15, s14, 31
	s_lshl_b64 s[22:23], s[14:15], 19
	s_add_u32 s22, s2, s22
	s_addc_u32 s23, s3, s23
	s_and_b64 s[24:25], s[4:5], exec
	s_cselect_b32 s15, s23, s11
	s_cselect_b32 s43, s22, s10
	s_add_u32 s24, s20, 0x40080
	s_addc_u32 s25, s21, 0
	s_add_u32 s44, s10, 0x100
	s_nop 7
	s_nop 7
	s_addc_u32 s45, s11, 0
	s_mov_b32 s46, -2
	v_readlane_b32 s50, v254, 54
	ds_read_b128 v[144:147], v151
	ds_read_b128 v[156:159], v151 offset:1024
	ds_read_b128 v[160:163], v151 offset:2048
	ds_read_b128 v[164:167], v151 offset:3072
	ds_read_b128 v[168:171], v152
	ds_read_b128 v[172:175], v152 offset:1024
	ds_read_b128 v[176:179], v152 offset:2048
	ds_read_b128 v[180:183], v152 offset:3072
	s_add_u32 s10, s24, 0xfffc0080
	s_addc_u32 s11, s25, -1
	s_cmp_eq_u32 s46, 12
	s_cselect_b32 s21, s17, s11
	s_cselect_b32 s20, s42, s10
	s_cselect_b32 s11, s15, s45
	s_cselect_b32 s10, s43, s44
	v_lshl_add_u64 v[216:217], s[24:25], 0, v[136:137]
	s_add_i32 m0, s28, 0xc000
	ds_read_b128 v[184:187], v153
	ds_read_b128 v[188:191], v153 offset:1024
	ds_read_b128 v[192:195], v153 offset:2048
	ds_read_b128 v[196:199], v153 offset:3072
	ds_read_b128 v[200:203], v153 offset:4096
	ds_read_b128 v[204:207], v153 offset:5120
	ds_read_b128 v[208:211], v153 offset:6144
	ds_read_b128 v[212:215], v153 offset:7168
	global_load_lds_dwordx4 v[216:217], off
	v_lshl_add_u64 v[216:217], s[24:25], 0, v[138:139]
	s_add_i32 m0, s28, 0xe000
	s_nop 0
	global_load_lds_dwordx4 v[216:217], off
	s_waitcnt vmcnt(8)
	s_waitcnt lgkmcnt(0)
	s_barrier
	s_setprio 1
	s_waitcnt lgkmcnt(0)
	v_mfma_f32_16x16x32_bf16 v[116:119], v[144:147], v[184:187], 0
	v_mfma_f32_16x16x32_bf16 v[112:115], v[160:163], v[184:187], 0
	v_mfma_f32_16x16x32_bf16 v[100:103], v[144:147], v[192:195], 0
	v_mfma_f32_16x16x32_bf16 v[96:99], v[160:163], v[192:195], 0
	v_mfma_f32_16x16x32_bf16 v[84:87], v[144:147], v[200:203], 0
	v_mfma_f32_16x16x32_bf16 v[80:83], v[160:163], v[200:203], 0
	v_mfma_f32_16x16x32_bf16 v[72:75], v[144:147], v[208:211], 0
	v_mfma_f32_16x16x32_bf16 v[64:67], v[160:163], v[208:211], 0
	v_mfma_f32_16x16x32_bf16 v[116:119], v[156:159], v[188:191], v[116:119]
	v_mfma_f32_16x16x32_bf16 v[112:115], v[164:167], v[188:191], v[112:115]
	v_mfma_f32_16x16x32_bf16 v[100:103], v[156:159], v[196:199], v[100:103]
	v_mfma_f32_16x16x32_bf16 v[96:99], v[164:167], v[196:199], v[96:99]
	v_mfma_f32_16x16x32_bf16 v[84:87], v[156:159], v[204:207], v[84:87]
	v_mfma_f32_16x16x32_bf16 v[80:83], v[164:167], v[204:207], v[80:83]
	v_mfma_f32_16x16x32_bf16 v[72:75], v[156:159], v[212:215], v[72:75]
	v_mfma_f32_16x16x32_bf16 v[64:67], v[164:167], v[212:215], v[64:67]
	s_setprio 0
	s_setprio 1
	v_mfma_f32_16x16x32_bf16 v[124:127], v[168:171], v[184:187], 0
	v_mfma_f32_16x16x32_bf16 v[120:123], v[176:179], v[184:187], 0
	v_mfma_f32_16x16x32_bf16 v[108:111], v[168:171], v[192:195], 0
	v_mfma_f32_16x16x32_bf16 v[104:107], v[176:179], v[192:195], 0
	v_mfma_f32_16x16x32_bf16 v[92:95], v[168:171], v[200:203], 0
	v_mfma_f32_16x16x32_bf16 v[88:91], v[176:179], v[200:203], 0
	v_mfma_f32_16x16x32_bf16 v[76:79], v[168:171], v[208:211], 0
	v_mfma_f32_16x16x32_bf16 v[68:71], v[176:179], v[208:211], 0
	v_mfma_f32_16x16x32_bf16 v[124:127], v[172:175], v[188:191], v[124:127]
	v_mfma_f32_16x16x32_bf16 v[120:123], v[180:183], v[188:191], v[120:123]
	v_mfma_f32_16x16x32_bf16 v[108:111], v[172:175], v[196:199], v[108:111]
	v_mfma_f32_16x16x32_bf16 v[104:107], v[180:183], v[196:199], v[104:107]
	v_mfma_f32_16x16x32_bf16 v[92:95], v[172:175], v[204:207], v[92:95]
	v_mfma_f32_16x16x32_bf16 v[88:91], v[180:183], v[204:207], v[88:91]
	v_mfma_f32_16x16x32_bf16 v[76:79], v[172:175], v[212:215], v[76:79]
	v_mfma_f32_16x16x32_bf16 v[68:71], v[180:183], v[212:215], v[68:71]
	s_setprio 0
	s_barrier
	s_add_i32 s47, s38, s50
	v_lshl_add_u64 v[216:217], s[10:11], 0, v[132:133]
	s_mov_b32 m0, s47
	ds_read_b128 v[184:187], v153 offset:16384
	ds_read_b128 v[188:191], v153 offset:17408
	ds_read_b128 v[192:195], v153 offset:18432
	ds_read_b128 v[196:199], v153 offset:19456
	ds_read_b128 v[200:203], v153 offset:20480
	ds_read_b128 v[204:207], v153 offset:21504
	ds_read_b128 v[208:211], v153 offset:22528
	ds_read_b128 v[212:215], v153 offset:23552
	global_load_lds_dwordx4 v[216:217], off
	s_add_i32 m0, s47, 0x2000
	s_add_u32 s48, s10, 0x40000
	v_lshl_add_u64 v[218:219], s[10:11], 0, v[128:129]
	s_addc_u32 s49, s11, 0
	s_add_i32 s47, s39, s50
	global_load_lds_dwordx4 v[218:219], off
	v_lshl_add_u64 v[220:221], s[48:49], 0, v[132:133]
	s_mov_b32 m0, s47
	v_lshl_add_u64 v[222:223], s[20:21], 0, v[130:131]
	global_load_lds_dwordx4 v[220:221], off
	v_lshl_add_u64 v[220:221], s[48:49], 0, v[128:129]
	s_add_i32 m0, s47, 0x2000
	s_nop 0
	global_load_lds_dwordx4 v[220:221], off
	v_lshl_add_u64 v[220:221], s[20:21], 0, v[134:135]
	s_mov_b32 m0, s28
	s_nop 0
	global_load_lds_dwordx4 v[220:221], off
	s_mov_b32 m0, s29
	s_nop 0
	global_load_lds_dwordx4 v[222:223], off
	s_waitcnt vmcnt(8)
	s_waitcnt lgkmcnt(0)
	s_barrier
	s_setprio 1
	s_waitcnt lgkmcnt(0)
	v_mfma_f32_16x16x32_bf16 v[56:59], v[144:147], v[184:187], 0
	v_mfma_f32_16x16x32_bf16 v[48:51], v[160:163], v[184:187], 0
	v_mfma_f32_16x16x32_bf16 v[40:43], v[144:147], v[192:195], 0
	v_mfma_f32_16x16x32_bf16 v[32:35], v[160:163], v[192:195], 0
	v_mfma_f32_16x16x32_bf16 v[24:27], v[144:147], v[200:203], 0
	v_mfma_f32_16x16x32_bf16 v[16:19], v[160:163], v[200:203], 0
	v_mfma_f32_16x16x32_bf16 v[8:11], v[144:147], v[208:211], 0
	v_mfma_f32_16x16x32_bf16 v[0:3], v[160:163], v[208:211], 0
	v_mfma_f32_16x16x32_bf16 v[56:59], v[156:159], v[188:191], v[56:59]
	v_mfma_f32_16x16x32_bf16 v[48:51], v[164:167], v[188:191], v[48:51]
	v_mfma_f32_16x16x32_bf16 v[40:43], v[156:159], v[196:199], v[40:43]
	v_mfma_f32_16x16x32_bf16 v[32:35], v[164:167], v[196:199], v[32:35]
	v_mfma_f32_16x16x32_bf16 v[24:27], v[156:159], v[204:207], v[24:27]
	v_mfma_f32_16x16x32_bf16 v[16:19], v[164:167], v[204:207], v[16:19]
	v_mfma_f32_16x16x32_bf16 v[8:11], v[156:159], v[212:215], v[8:11]
	v_mfma_f32_16x16x32_bf16 v[0:3], v[164:167], v[212:215], v[0:3]
	s_setprio 0
	s_setprio 1
	v_mfma_f32_16x16x32_bf16 v[60:63], v[168:171], v[184:187], 0
	v_mfma_f32_16x16x32_bf16 v[52:55], v[176:179], v[184:187], 0
	v_mfma_f32_16x16x32_bf16 v[44:47], v[168:171], v[192:195], 0
	v_mfma_f32_16x16x32_bf16 v[36:39], v[176:179], v[192:195], 0
	v_mfma_f32_16x16x32_bf16 v[28:31], v[168:171], v[200:203], 0
	v_mfma_f32_16x16x32_bf16 v[20:23], v[176:179], v[200:203], 0
	v_mfma_f32_16x16x32_bf16 v[12:15], v[168:171], v[208:211], 0
	v_mfma_f32_16x16x32_bf16 v[4:7], v[176:179], v[208:211], 0
	v_mfma_f32_16x16x32_bf16 v[60:63], v[172:175], v[188:191], v[60:63]
	v_mfma_f32_16x16x32_bf16 v[52:55], v[180:183], v[188:191], v[52:55]
	v_mfma_f32_16x16x32_bf16 v[44:47], v[172:175], v[196:199], v[44:47]
	v_mfma_f32_16x16x32_bf16 v[36:39], v[180:183], v[196:199], v[36:39]
	v_mfma_f32_16x16x32_bf16 v[28:31], v[172:175], v[204:207], v[28:31]
	v_mfma_f32_16x16x32_bf16 v[20:23], v[180:183], v[204:207], v[20:23]
	v_mfma_f32_16x16x32_bf16 v[12:15], v[172:175], v[212:215], v[12:15]
	v_mfma_f32_16x16x32_bf16 v[4:7], v[180:183], v[212:215], v[4:7]
	s_setprio 0
	s_barrier
	s_add_i32 s47, 0, 0x18000
	v_add_u32_e32 v155, s47, v149
	s_add_i32 s48, 0, 0x1c000
	ds_read_b128 v[144:147], v155
	ds_read_b128 v[156:159], v155 offset:1024
	ds_read_b128 v[160:163], v155 offset:2048
	ds_read_b128 v[164:167], v155 offset:3072
	v_add_u32_e32 v155, s48, v149
	ds_read_b128 v[168:171], v155
	ds_read_b128 v[172:175], v155 offset:1024
	ds_read_b128 v[176:179], v155 offset:2048
	ds_read_b128 v[180:183], v155 offset:3072
	s_add_u32 s20, s20, 0x40000
	s_addc_u32 s21, s21, 0
	s_mov_b32 m0, s30
	v_lshl_add_u64 v[224:225], s[20:21], 0, v[134:135]
	ds_read_b128 v[184:187], v153 offset:32768
	ds_read_b128 v[188:191], v153 offset:33792
	ds_read_b128 v[192:195], v153 offset:34816
	ds_read_b128 v[196:199], v153 offset:35840
	ds_read_b128 v[200:203], v153 offset:36864
	ds_read_b128 v[204:207], v153 offset:37888
	ds_read_b128 v[208:211], v153 offset:38912
	ds_read_b128 v[212:215], v153 offset:39936
	global_load_lds_dwordx4 v[224:225], off
	v_lshl_add_u64 v[224:225], s[20:21], 0, v[130:131]
	s_mov_b32 m0, s31
	s_nop 0
	global_load_lds_dwordx4 v[224:225], off
	s_waitcnt vmcnt(8)
	s_waitcnt lgkmcnt(0)
	s_barrier
	s_setprio 1
	s_waitcnt lgkmcnt(0)
	v_mfma_f32_16x16x32_bf16 v[116:119], v[144:147], v[184:187], v[116:119]
	v_mfma_f32_16x16x32_bf16 v[112:115], v[160:163], v[184:187], v[112:115]
	v_mfma_f32_16x16x32_bf16 v[100:103], v[144:147], v[192:195], v[100:103]
	v_mfma_f32_16x16x32_bf16 v[96:99], v[160:163], v[192:195], v[96:99]
	v_mfma_f32_16x16x32_bf16 v[84:87], v[144:147], v[200:203], v[84:87]
	v_mfma_f32_16x16x32_bf16 v[80:83], v[160:163], v[200:203], v[80:83]
	v_mfma_f32_16x16x32_bf16 v[72:75], v[144:147], v[208:211], v[72:75]
	v_mfma_f32_16x16x32_bf16 v[64:67], v[160:163], v[208:211], v[64:67]
	v_mfma_f32_16x16x32_bf16 v[116:119], v[156:159], v[188:191], v[116:119]
	v_mfma_f32_16x16x32_bf16 v[112:115], v[164:167], v[188:191], v[112:115]
	v_mfma_f32_16x16x32_bf16 v[100:103], v[156:159], v[196:199], v[100:103]
	v_mfma_f32_16x16x32_bf16 v[96:99], v[164:167], v[196:199], v[96:99]
	v_mfma_f32_16x16x32_bf16 v[84:87], v[156:159], v[204:207], v[84:87]
	v_mfma_f32_16x16x32_bf16 v[80:83], v[164:167], v[204:207], v[80:83]
	v_mfma_f32_16x16x32_bf16 v[72:75], v[156:159], v[212:215], v[72:75]
	v_mfma_f32_16x16x32_bf16 v[64:67], v[164:167], v[212:215], v[64:67]
	s_setprio 0
	s_setprio 1
	v_mfma_f32_16x16x32_bf16 v[124:127], v[168:171], v[184:187], v[124:127]
	v_mfma_f32_16x16x32_bf16 v[120:123], v[176:179], v[184:187], v[120:123]
	v_mfma_f32_16x16x32_bf16 v[108:111], v[168:171], v[192:195], v[108:111]
	v_mfma_f32_16x16x32_bf16 v[104:107], v[176:179], v[192:195], v[104:107]
	v_mfma_f32_16x16x32_bf16 v[92:95], v[168:171], v[200:203], v[92:95]
	v_mfma_f32_16x16x32_bf16 v[88:91], v[176:179], v[200:203], v[88:91]
	v_mfma_f32_16x16x32_bf16 v[76:79], v[168:171], v[208:211], v[76:79]
	v_mfma_f32_16x16x32_bf16 v[68:71], v[176:179], v[208:211], v[68:71]
	v_mfma_f32_16x16x32_bf16 v[124:127], v[172:175], v[188:191], v[124:127]
	v_mfma_f32_16x16x32_bf16 v[120:123], v[180:183], v[188:191], v[120:123]
	v_mfma_f32_16x16x32_bf16 v[108:111], v[172:175], v[196:199], v[108:111]
	v_mfma_f32_16x16x32_bf16 v[104:107], v[180:183], v[196:199], v[104:107]
	v_mfma_f32_16x16x32_bf16 v[92:95], v[172:175], v[204:207], v[92:95]
	v_mfma_f32_16x16x32_bf16 v[88:91], v[180:183], v[204:207], v[88:91]
	v_mfma_f32_16x16x32_bf16 v[76:79], v[172:175], v[212:215], v[76:79]
	v_mfma_f32_16x16x32_bf16 v[68:71], v[180:183], v[212:215], v[68:71]
	s_setprio 0
	s_barrier
	s_add_i32 s20, s47, s50
	v_lshl_add_u64 v[216:217], v[216:217], 0, s[12:13]
	s_mov_b32 m0, s20
	ds_read_b128 v[184:187], v153 offset:49152
	ds_read_b128 v[188:191], v153 offset:50176
	ds_read_b128 v[192:195], v153 offset:51200
	ds_read_b128 v[196:199], v153 offset:52224
	ds_read_b128 v[200:203], v153 offset:53248
	ds_read_b128 v[204:207], v153 offset:54272
	ds_read_b128 v[208:211], v153 offset:55296
	ds_read_b128 v[212:215], v153 offset:56320
	global_load_lds_dwordx4 v[216:217], off
	s_add_i32 m0, s20, 0x2000
	s_add_u32 s10, s10, 0x40080
	v_lshl_add_u64 v[216:217], v[218:219], 0, s[12:13]
	s_addc_u32 s11, s11, 0
	s_add_i32 s20, s48, s50
	global_load_lds_dwordx4 v[216:217], off
	v_lshl_add_u64 v[216:217], s[10:11], 0, v[132:133]
	s_mov_b32 m0, s20
	s_nop 0
	global_load_lds_dwordx4 v[216:217], off
	v_lshl_add_u64 v[216:217], s[10:11], 0, v[128:129]
	s_add_i32 m0, s20, 0x2000
	s_nop 0
	global_load_lds_dwordx4 v[216:217], off
	v_lshl_add_u64 v[216:217], v[220:221], 0, s[12:13]
	s_mov_b32 m0, s34
	s_nop 0
	global_load_lds_dwordx4 v[216:217], off
	v_lshl_add_u64 v[216:217], v[222:223], 0, s[12:13]
	s_mov_b32 m0, s35
	s_nop 0
	global_load_lds_dwordx4 v[216:217], off
	s_waitcnt vmcnt(8)
	s_waitcnt lgkmcnt(0)
	s_barrier
	s_setprio 1
	s_waitcnt lgkmcnt(0)
	v_mfma_f32_16x16x32_bf16 v[56:59], v[144:147], v[184:187], v[56:59]
	v_mfma_f32_16x16x32_bf16 v[48:51], v[160:163], v[184:187], v[48:51]
	v_mfma_f32_16x16x32_bf16 v[40:43], v[144:147], v[192:195], v[40:43]
	v_mfma_f32_16x16x32_bf16 v[32:35], v[160:163], v[192:195], v[32:35]
	v_mfma_f32_16x16x32_bf16 v[24:27], v[144:147], v[200:203], v[24:27]
	v_mfma_f32_16x16x32_bf16 v[16:19], v[160:163], v[200:203], v[16:19]
	v_mfma_f32_16x16x32_bf16 v[8:11], v[144:147], v[208:211], v[8:11]
	v_mfma_f32_16x16x32_bf16 v[0:3], v[160:163], v[208:211], v[0:3]
	v_mfma_f32_16x16x32_bf16 v[56:59], v[156:159], v[188:191], v[56:59]
	v_mfma_f32_16x16x32_bf16 v[48:51], v[164:167], v[188:191], v[48:51]
	v_mfma_f32_16x16x32_bf16 v[40:43], v[156:159], v[196:199], v[40:43]
	v_mfma_f32_16x16x32_bf16 v[32:35], v[164:167], v[196:199], v[32:35]
	v_mfma_f32_16x16x32_bf16 v[24:27], v[156:159], v[204:207], v[24:27]
	v_mfma_f32_16x16x32_bf16 v[16:19], v[164:167], v[204:207], v[16:19]
	v_mfma_f32_16x16x32_bf16 v[8:11], v[156:159], v[212:215], v[8:11]
	v_mfma_f32_16x16x32_bf16 v[0:3], v[164:167], v[212:215], v[0:3]
	s_setprio 0
	s_setprio 1
	v_mfma_f32_16x16x32_bf16 v[60:63], v[168:171], v[184:187], v[60:63]
	v_mfma_f32_16x16x32_bf16 v[52:55], v[176:179], v[184:187], v[52:55]
	v_mfma_f32_16x16x32_bf16 v[44:47], v[168:171], v[192:195], v[44:47]
	v_mfma_f32_16x16x32_bf16 v[36:39], v[176:179], v[192:195], v[36:39]
	v_mfma_f32_16x16x32_bf16 v[28:31], v[168:171], v[200:203], v[28:31]
	v_mfma_f32_16x16x32_bf16 v[20:23], v[176:179], v[200:203], v[20:23]
	v_mfma_f32_16x16x32_bf16 v[12:15], v[168:171], v[208:211], v[12:15]
	v_mfma_f32_16x16x32_bf16 v[4:7], v[176:179], v[208:211], v[4:7]
	v_mfma_f32_16x16x32_bf16 v[60:63], v[172:175], v[188:191], v[60:63]
	v_mfma_f32_16x16x32_bf16 v[52:55], v[180:183], v[188:191], v[52:55]
	v_mfma_f32_16x16x32_bf16 v[44:47], v[172:175], v[196:199], v[44:47]
	v_mfma_f32_16x16x32_bf16 v[36:39], v[180:183], v[196:199], v[36:39]
	v_mfma_f32_16x16x32_bf16 v[28:31], v[172:175], v[204:207], v[28:31]
	v_mfma_f32_16x16x32_bf16 v[20:23], v[180:183], v[204:207], v[20:23]
	v_mfma_f32_16x16x32_bf16 v[12:15], v[172:175], v[212:215], v[12:15]
	v_mfma_f32_16x16x32_bf16 v[4:7], v[180:183], v[212:215], v[4:7]
	s_setprio 0
	s_barrier
	s_add_i32 s46, s46, 2
	s_add_u32 s24, s24, 0x100
	s_addc_u32 s25, s25, 0
	s_add_u32 s44, s44, 0x100
	s_addc_u32 s45, s45, 0
	s_cmp_gt_u32 s46, 13

.LBB0_1085:
	s_add_u32 s44, s22, 0x100
	s_nop 7
	s_nop 7
	s_addc_u32 s45, s23, 0
	s_mov_b32 s46, -2
	v_readlane_b32 s49, v254, 54
	ds_read_b128 v[140:143], v155
	ds_read_b128 v[144:147], v155 offset:1024
	ds_read_b128 v[148:151], v155 offset:2048
	ds_read_b128 v[158:161], v155 offset:3072
	ds_read_b128 v[162:165], v156
	ds_read_b128 v[166:169], v156 offset:1024
	ds_read_b128 v[170:173], v156 offset:2048
	ds_read_b128 v[174:177], v156 offset:3072
	s_add_u32 s22, s20, 0x100
	s_addc_u32 s23, s21, 0
	s_cmp_eq_u32 s46, 40
	s_cselect_b32 s27, s5, s23
	s_cselect_b32 s26, s4, s22
	s_cselect_b32 s25, s19, s45
	s_cselect_b32 s24, s18, s44
	v_lshl_add_u64 v[210:211], s[20:21], 0, v[132:133]
	s_add_i32 m0, s29, 0xc000
	ds_read_b128 v[178:181], v157
	ds_read_b128 v[182:185], v157 offset:1024
	ds_read_b128 v[186:189], v157 offset:2048
	ds_read_b128 v[190:193], v157 offset:3072
	ds_read_b128 v[194:197], v157 offset:4096
	ds_read_b128 v[198:201], v157 offset:5120
	ds_read_b128 v[202:205], v157 offset:6144
	ds_read_b128 v[206:209], v157 offset:7168
	global_load_lds_dwordx4 v[210:211], off
	v_lshl_add_u64 v[210:211], s[20:21], 0, v[134:135]
	s_add_i32 m0, s29, 0xe000
	s_nop 0
	global_load_lds_dwordx4 v[210:211], off
	s_waitcnt vmcnt(8)
	s_waitcnt lgkmcnt(0)
	s_barrier
	s_setprio 1
	s_waitcnt lgkmcnt(0)
	v_mfma_f32_16x16x32_bf16 v[124:127], v[140:143], v[178:181], 0
	v_mfma_f32_16x16x32_bf16 v[120:123], v[148:151], v[178:181], 0
	v_mfma_f32_16x16x32_bf16 v[116:119], v[140:143], v[186:189], 0
	v_mfma_f32_16x16x32_bf16 v[112:115], v[148:151], v[186:189], 0
	v_mfma_f32_16x16x32_bf16 v[104:107], v[140:143], v[194:197], 0
	v_mfma_f32_16x16x32_bf16 v[96:99], v[148:151], v[194:197], 0
	v_mfma_f32_16x16x32_bf16 v[88:91], v[140:143], v[202:205], 0
	v_mfma_f32_16x16x32_bf16 v[80:83], v[148:151], v[202:205], 0
	v_mfma_f32_16x16x32_bf16 v[124:127], v[144:147], v[182:185], v[124:127]
	v_mfma_f32_16x16x32_bf16 v[120:123], v[158:161], v[182:185], v[120:123]
	v_mfma_f32_16x16x32_bf16 v[116:119], v[144:147], v[190:193], v[116:119]
	v_mfma_f32_16x16x32_bf16 v[112:115], v[158:161], v[190:193], v[112:115]
	v_mfma_f32_16x16x32_bf16 v[104:107], v[144:147], v[198:201], v[104:107]
	v_mfma_f32_16x16x32_bf16 v[96:99], v[158:161], v[198:201], v[96:99]
	v_mfma_f32_16x16x32_bf16 v[88:91], v[144:147], v[206:209], v[88:91]
	v_mfma_f32_16x16x32_bf16 v[80:83], v[158:161], v[206:209], v[80:83]
	s_setprio 0
	s_setprio 1
	v_mfma_f32_16x16x32_bf16 v[108:111], v[162:165], v[178:181], 0
	v_mfma_f32_16x16x32_bf16 v[100:103], v[170:173], v[178:181], 0
	v_mfma_f32_16x16x32_bf16 v[92:95], v[162:165], v[186:189], 0
	v_mfma_f32_16x16x32_bf16 v[84:87], v[170:173], v[186:189], 0
	v_mfma_f32_16x16x32_bf16 v[76:79], v[162:165], v[194:197], 0
	v_mfma_f32_16x16x32_bf16 v[72:75], v[170:173], v[194:197], 0
	v_mfma_f32_16x16x32_bf16 v[68:71], v[162:165], v[202:205], 0
	v_mfma_f32_16x16x32_bf16 v[64:67], v[170:173], v[202:205], 0
	v_mfma_f32_16x16x32_bf16 v[108:111], v[166:169], v[182:185], v[108:111]
	v_mfma_f32_16x16x32_bf16 v[100:103], v[174:177], v[182:185], v[100:103]
	v_mfma_f32_16x16x32_bf16 v[92:95], v[166:169], v[190:193], v[92:95]
	v_mfma_f32_16x16x32_bf16 v[84:87], v[174:177], v[190:193], v[84:87]
	v_mfma_f32_16x16x32_bf16 v[76:79], v[166:169], v[198:201], v[76:79]
	v_mfma_f32_16x16x32_bf16 v[72:75], v[174:177], v[198:201], v[72:75]
	v_mfma_f32_16x16x32_bf16 v[68:71], v[166:169], v[206:209], v[68:71]
	v_mfma_f32_16x16x32_bf16 v[64:67], v[174:177], v[206:209], v[64:67]
	s_setprio 0
	s_barrier
	s_add_i32 s20, s38, s49
	v_lshl_add_u64 v[210:211], s[24:25], 0, v[128:129]
	s_mov_b32 m0, s20
	ds_read_b128 v[178:181], v157 offset:16384
	ds_read_b128 v[182:185], v157 offset:17408
	ds_read_b128 v[186:189], v157 offset:18432
	ds_read_b128 v[190:193], v157 offset:19456
	ds_read_b128 v[194:197], v157 offset:20480
	ds_read_b128 v[198:201], v157 offset:21504
	ds_read_b128 v[202:205], v157 offset:22528
	ds_read_b128 v[206:209], v157 offset:23552
	global_load_lds_dwordx4 v[210:211], off
	s_add_i32 m0, s20, 0x2000
	s_add_u32 s20, s24, 0xb0000
	v_lshl_add_u64 v[212:213], s[24:25], 0, v[130:131]
	s_addc_u32 s21, s25, 0
	s_add_i32 s47, s39, s49
	global_load_lds_dwordx4 v[212:213], off
	v_lshl_add_u64 v[214:215], s[20:21], 0, v[128:129]
	s_mov_b32 m0, s47
	v_lshl_add_u64 v[216:217], s[26:27], 0, v[130:131]
	global_load_lds_dwordx4 v[214:215], off
	v_lshl_add_u64 v[214:215], s[20:21], 0, v[130:131]
	s_add_i32 m0, s47, 0x2000
	s_nop 0
	global_load_lds_dwordx4 v[214:215], off
	v_lshl_add_u64 v[214:215], s[26:27], 0, v[128:129]
	s_mov_b32 m0, s29
	s_nop 0
	global_load_lds_dwordx4 v[214:215], off
	s_mov_b32 m0, s30
	s_nop 0
	global_load_lds_dwordx4 v[216:217], off
	s_waitcnt vmcnt(8)
	s_waitcnt lgkmcnt(0)
	s_barrier
	s_setprio 1
	s_waitcnt lgkmcnt(0)
	v_mfma_f32_16x16x32_bf16 v[60:63], v[140:143], v[178:181], 0
	v_mfma_f32_16x16x32_bf16 v[56:59], v[148:151], v[178:181], 0
	v_mfma_f32_16x16x32_bf16 v[52:55], v[140:143], v[186:189], 0
	v_mfma_f32_16x16x32_bf16 v[44:47], v[148:151], v[186:189], 0
	v_mfma_f32_16x16x32_bf16 v[36:39], v[140:143], v[194:197], 0
	v_mfma_f32_16x16x32_bf16 v[28:31], v[148:151], v[194:197], 0
	v_mfma_f32_16x16x32_bf16 v[20:23], v[140:143], v[202:205], 0
	v_mfma_f32_16x16x32_bf16 v[8:11], v[148:151], v[202:205], 0
	v_mfma_f32_16x16x32_bf16 v[60:63], v[144:147], v[182:185], v[60:63]
	v_mfma_f32_16x16x32_bf16 v[56:59], v[158:161], v[182:185], v[56:59]
	v_mfma_f32_16x16x32_bf16 v[52:55], v[144:147], v[190:193], v[52:55]
	v_mfma_f32_16x16x32_bf16 v[44:47], v[158:161], v[190:193], v[44:47]
	v_mfma_f32_16x16x32_bf16 v[36:39], v[144:147], v[198:201], v[36:39]
	v_mfma_f32_16x16x32_bf16 v[28:31], v[158:161], v[198:201], v[28:31]
	v_mfma_f32_16x16x32_bf16 v[20:23], v[144:147], v[206:209], v[20:23]
	v_mfma_f32_16x16x32_bf16 v[8:11], v[158:161], v[206:209], v[8:11]
	s_setprio 0
	s_setprio 1
	v_mfma_f32_16x16x32_bf16 v[48:51], v[162:165], v[178:181], 0
	v_mfma_f32_16x16x32_bf16 v[40:43], v[170:173], v[178:181], 0
	v_mfma_f32_16x16x32_bf16 v[32:35], v[162:165], v[186:189], 0
	v_mfma_f32_16x16x32_bf16 v[24:27], v[170:173], v[186:189], 0
	v_mfma_f32_16x16x32_bf16 v[16:19], v[162:165], v[194:197], 0
	v_mfma_f32_16x16x32_bf16 v[12:15], v[170:173], v[194:197], 0
	v_mfma_f32_16x16x32_bf16 v[4:7], v[162:165], v[202:205], 0
	v_mfma_f32_16x16x32_bf16 v[0:3], v[170:173], v[202:205], 0
	v_mfma_f32_16x16x32_bf16 v[48:51], v[166:169], v[182:185], v[48:51]
	v_mfma_f32_16x16x32_bf16 v[40:43], v[174:177], v[182:185], v[40:43]
	v_mfma_f32_16x16x32_bf16 v[32:35], v[166:169], v[190:193], v[32:35]
	v_mfma_f32_16x16x32_bf16 v[24:27], v[174:177], v[190:193], v[24:27]
	v_mfma_f32_16x16x32_bf16 v[16:19], v[166:169], v[198:201], v[16:19]
	v_mfma_f32_16x16x32_bf16 v[12:15], v[174:177], v[198:201], v[12:15]
	v_mfma_f32_16x16x32_bf16 v[4:7], v[166:169], v[206:209], v[4:7]
	v_mfma_f32_16x16x32_bf16 v[0:3], v[174:177], v[206:209], v[0:3]
	s_setprio 0
	s_barrier
	s_add_i32 s47, 0, 0x18000
	s_add_i32 s48, 0, 0x1c000
	v_add_u32_e32 v158, s47, v153
	v_add_u32_e32 v174, s48, v153
	ds_read_b128 v[140:143], v158
	ds_read_b128 v[144:147], v158 offset:1024
	ds_read_b128 v[148:151], v158 offset:2048
	ds_read_b128 v[158:161], v158 offset:3072
	ds_read_b128 v[162:165], v174
	ds_read_b128 v[166:169], v174 offset:1024
	ds_read_b128 v[170:173], v174 offset:2048
	ds_read_b128 v[174:177], v174 offset:3072
	s_add_u32 s20, s26, 0xb0000
	s_addc_u32 s21, s27, 0
	s_mov_b32 m0, s31
	v_lshl_add_u64 v[218:219], s[20:21], 0, v[128:129]
	ds_read_b128 v[178:181], v157 offset:32768
	ds_read_b128 v[182:185], v157 offset:33792
	ds_read_b128 v[186:189], v157 offset:34816
	ds_read_b128 v[190:193], v157 offset:35840
	ds_read_b128 v[194:197], v157 offset:36864
	ds_read_b128 v[198:201], v157 offset:37888
	ds_read_b128 v[202:205], v157 offset:38912
	ds_read_b128 v[206:209], v157 offset:39936
	global_load_lds_dwordx4 v[218:219], off
	v_lshl_add_u64 v[218:219], s[20:21], 0, v[130:131]
	s_mov_b32 m0, s33
	s_nop 0
	global_load_lds_dwordx4 v[218:219], off
	s_waitcnt vmcnt(8)
	s_waitcnt lgkmcnt(0)
	s_barrier
	s_setprio 1
	s_waitcnt lgkmcnt(0)
	v_mfma_f32_16x16x32_bf16 v[124:127], v[140:143], v[178:181], v[124:127]
	v_mfma_f32_16x16x32_bf16 v[120:123], v[148:151], v[178:181], v[120:123]
	v_mfma_f32_16x16x32_bf16 v[116:119], v[140:143], v[186:189], v[116:119]
	v_mfma_f32_16x16x32_bf16 v[112:115], v[148:151], v[186:189], v[112:115]
	v_mfma_f32_16x16x32_bf16 v[104:107], v[140:143], v[194:197], v[104:107]
	v_mfma_f32_16x16x32_bf16 v[96:99], v[148:151], v[194:197], v[96:99]
	v_mfma_f32_16x16x32_bf16 v[88:91], v[140:143], v[202:205], v[88:91]
	v_mfma_f32_16x16x32_bf16 v[80:83], v[148:151], v[202:205], v[80:83]
	v_mfma_f32_16x16x32_bf16 v[124:127], v[144:147], v[182:185], v[124:127]
	v_mfma_f32_16x16x32_bf16 v[120:123], v[158:161], v[182:185], v[120:123]
	v_mfma_f32_16x16x32_bf16 v[116:119], v[144:147], v[190:193], v[116:119]
	v_mfma_f32_16x16x32_bf16 v[112:115], v[158:161], v[190:193], v[112:115]
	v_mfma_f32_16x16x32_bf16 v[104:107], v[144:147], v[198:201], v[104:107]
	v_mfma_f32_16x16x32_bf16 v[96:99], v[158:161], v[198:201], v[96:99]
	v_mfma_f32_16x16x32_bf16 v[88:91], v[144:147], v[206:209], v[88:91]
	v_mfma_f32_16x16x32_bf16 v[80:83], v[158:161], v[206:209], v[80:83]
	s_setprio 0
	s_setprio 1
	v_mfma_f32_16x16x32_bf16 v[108:111], v[162:165], v[178:181], v[108:111]
	v_mfma_f32_16x16x32_bf16 v[100:103], v[170:173], v[178:181], v[100:103]
	v_mfma_f32_16x16x32_bf16 v[92:95], v[162:165], v[186:189], v[92:95]
	v_mfma_f32_16x16x32_bf16 v[84:87], v[170:173], v[186:189], v[84:87]
	v_mfma_f32_16x16x32_bf16 v[76:79], v[162:165], v[194:197], v[76:79]
	v_mfma_f32_16x16x32_bf16 v[72:75], v[170:173], v[194:197], v[72:75]
	v_mfma_f32_16x16x32_bf16 v[68:71], v[162:165], v[202:205], v[68:71]
	v_mfma_f32_16x16x32_bf16 v[64:67], v[170:173], v[202:205], v[64:67]
	v_mfma_f32_16x16x32_bf16 v[108:111], v[166:169], v[182:185], v[108:111]
	v_mfma_f32_16x16x32_bf16 v[100:103], v[174:177], v[182:185], v[100:103]
	v_mfma_f32_16x16x32_bf16 v[92:95], v[166:169], v[190:193], v[92:95]
	v_mfma_f32_16x16x32_bf16 v[84:87], v[174:177], v[190:193], v[84:87]
	v_mfma_f32_16x16x32_bf16 v[76:79], v[166:169], v[198:201], v[76:79]
	v_mfma_f32_16x16x32_bf16 v[72:75], v[174:177], v[198:201], v[72:75]
	v_mfma_f32_16x16x32_bf16 v[68:71], v[166:169], v[206:209], v[68:71]
	v_mfma_f32_16x16x32_bf16 v[64:67], v[174:177], v[206:209], v[64:67]
	s_setprio 0
	s_barrier
	s_add_i32 s20, s47, s49
	v_lshl_add_u64 v[210:211], v[210:211], 0, s[10:11]
	s_mov_b32 m0, s20
	ds_read_b128 v[178:181], v157 offset:49152
	ds_read_b128 v[182:185], v157 offset:50176
	ds_read_b128 v[186:189], v157 offset:51200
	ds_read_b128 v[190:193], v157 offset:52224
	ds_read_b128 v[194:197], v157 offset:53248
	ds_read_b128 v[198:201], v157 offset:54272
	ds_read_b128 v[202:205], v157 offset:55296
	ds_read_b128 v[206:209], v157 offset:56320
	global_load_lds_dwordx4 v[210:211], off
	s_add_i32 m0, s20, 0x2000
	s_add_u32 s20, s24, 0xb0080
	v_lshl_add_u64 v[210:211], v[212:213], 0, s[10:11]
	s_addc_u32 s21, s25, 0
	s_add_i32 s24, s48, s49
	global_load_lds_dwordx4 v[210:211], off
	v_lshl_add_u64 v[210:211], s[20:21], 0, v[128:129]
	s_mov_b32 m0, s24
	s_nop 0
	global_load_lds_dwordx4 v[210:211], off
	v_lshl_add_u64 v[210:211], s[20:21], 0, v[130:131]
	s_add_i32 m0, s24, 0x2000
	s_nop 0
	global_load_lds_dwordx4 v[210:211], off
	v_lshl_add_u64 v[210:211], v[214:215], 0, s[10:11]
	s_mov_b32 m0, s35
	s_nop 0
	global_load_lds_dwordx4 v[210:211], off
	v_lshl_add_u64 v[210:211], v[216:217], 0, s[10:11]
	s_mov_b32 m0, s36
	s_nop 0
	global_load_lds_dwordx4 v[210:211], off
	s_waitcnt vmcnt(8)
	s_waitcnt lgkmcnt(0)
	s_barrier
	s_setprio 1
	s_waitcnt lgkmcnt(0)
	v_mfma_f32_16x16x32_bf16 v[60:63], v[140:143], v[178:181], v[60:63]
	v_mfma_f32_16x16x32_bf16 v[56:59], v[148:151], v[178:181], v[56:59]
	v_mfma_f32_16x16x32_bf16 v[52:55], v[140:143], v[186:189], v[52:55]
	v_mfma_f32_16x16x32_bf16 v[44:47], v[148:151], v[186:189], v[44:47]
	v_mfma_f32_16x16x32_bf16 v[36:39], v[140:143], v[194:197], v[36:39]
	v_mfma_f32_16x16x32_bf16 v[28:31], v[148:151], v[194:197], v[28:31]
	v_mfma_f32_16x16x32_bf16 v[20:23], v[140:143], v[202:205], v[20:23]
	v_mfma_f32_16x16x32_bf16 v[8:11], v[148:151], v[202:205], v[8:11]
	v_mfma_f32_16x16x32_bf16 v[60:63], v[144:147], v[182:185], v[60:63]
	v_mfma_f32_16x16x32_bf16 v[56:59], v[158:161], v[182:185], v[56:59]
	v_mfma_f32_16x16x32_bf16 v[52:55], v[144:147], v[190:193], v[52:55]
	v_mfma_f32_16x16x32_bf16 v[44:47], v[158:161], v[190:193], v[44:47]
	v_mfma_f32_16x16x32_bf16 v[36:39], v[144:147], v[198:201], v[36:39]
	v_mfma_f32_16x16x32_bf16 v[28:31], v[158:161], v[198:201], v[28:31]
	v_mfma_f32_16x16x32_bf16 v[20:23], v[144:147], v[206:209], v[20:23]
	v_mfma_f32_16x16x32_bf16 v[8:11], v[158:161], v[206:209], v[8:11]
	s_setprio 0
	s_setprio 1
	v_mfma_f32_16x16x32_bf16 v[48:51], v[162:165], v[178:181], v[48:51]
	v_mfma_f32_16x16x32_bf16 v[40:43], v[170:173], v[178:181], v[40:43]
	v_mfma_f32_16x16x32_bf16 v[32:35], v[162:165], v[186:189], v[32:35]
	v_mfma_f32_16x16x32_bf16 v[24:27], v[170:173], v[186:189], v[24:27]
	v_mfma_f32_16x16x32_bf16 v[16:19], v[162:165], v[194:197], v[16:19]
	v_mfma_f32_16x16x32_bf16 v[12:15], v[170:173], v[194:197], v[12:15]
	v_mfma_f32_16x16x32_bf16 v[4:7], v[162:165], v[202:205], v[4:7]
	v_mfma_f32_16x16x32_bf16 v[0:3], v[170:173], v[202:205], v[0:3]
	v_mfma_f32_16x16x32_bf16 v[48:51], v[166:169], v[182:185], v[48:51]
	v_mfma_f32_16x16x32_bf16 v[40:43], v[174:177], v[182:185], v[40:43]
	v_mfma_f32_16x16x32_bf16 v[32:35], v[166:169], v[190:193], v[32:35]
	v_mfma_f32_16x16x32_bf16 v[24:27], v[174:177], v[190:193], v[24:27]
	v_mfma_f32_16x16x32_bf16 v[16:19], v[166:169], v[198:201], v[16:19]
	v_mfma_f32_16x16x32_bf16 v[12:15], v[174:177], v[198:201], v[12:15]
	v_mfma_f32_16x16x32_bf16 v[4:7], v[166:169], v[206:209], v[4:7]
	v_mfma_f32_16x16x32_bf16 v[0:3], v[174:177], v[206:209], v[0:3]
	s_setprio 0
	s_barrier
	s_add_i32 s46, s46, 2
	s_add_u32 s44, s44, 0x100
	s_addc_u32 s45, s45, 0
	s_cmp_gt_u32 s46, 41
	s_mov_b64 s[20:21], s[22:23]
